# peephole: 40 single wait-state s_nop 0 (after packed/transcendental producers) in the router, conv and GLU/SwiGLU code filled with the next independent VALU instruction
# speedup vs baseline: 1.0019x; 1.0019x over previous
; DI unsigned pk2(float a, float b) { fl2_t f = {a, b}; bf2_t r = __builtin_convertvector(f, bf2_t); return __builtin_bit_cast(unsigned, r); }
; DI void phase2(const Params& p, char* lds) {
;     ...
;       const int j = nt - 12, row = tid & 127, hf = tid >> 7;
;       bfr* dst = (bfr*)(ws + WS_Z) + (size_t)(t0h + row) * 512 + j * 64 + hf * 32;
; #pragma unroll
;       for (int q = 0; q < 4; ++q) {
;         float z[8];
; #pragma unroll
;         for (int u = 0; u < 2; ++u) {
;           float4 a = cs4(Cs, row, hf * 32 + q * 8 + u * 4);
;           float4 g = cs4(Cs, row, 64 + hf * 32 + q * 8 + u * 4);
;           z[u * 4 + 0] = a.x / (1.f + __expf(-g.x)); z[u * 4 + 1] = a.y / (1.f + __expf(-g.y));
;           z[u * 4 + 2] = a.z / (1.f + __expf(-g.z)); z[u * 4 + 3] = a.w / (1.f + __expf(-g.w));
;         }
;         u32x4 o; o[0] = pk2(z[0], z[1]); o[1] = pk2(z[2], z[3]); o[2] = pk2(z[4], z[5]); o[3] = pk2(z[6], z[7]);
;         *(u32x4*)(dst + q * 8) = o;
;       }
.LBB0_125:
	s_cmp_gt_u32 s3, 11
	s_cbranch_scc0 .LBB0_127
	v_add_u32_e32 v2, s44, v166
	ds_read_b128 v[20:23], v167 offset:128
	v_ashrrev_i32_e32 v3, 31, v2
	v_lshlrev_b64 v[2:3], 10, v[2:3]
	s_lshl_b32 s8, s40, 7
	v_lshl_add_u64 v[2:3], s[14:15], 0, v[2:3]
	s_addk_i32 s8, 0xfd00
	v_lshl_add_u64 v[2:3], s[8:9], 1, v[2:3]
	v_lshlrev_b32_e32 v150, 1, v156
	v_lshl_add_u64 v[18:19], v[2:3], 0, v[150:151]
	s_waitcnt lgkmcnt(0)
	v_lshlrev_b32_e32 v2, 16, v20
	v_and_b32_e32 v3, 0xffff0000, v20
	v_mul_f32_e32 v2, 0xbfb8aa3b, v2
	v_exp_f32_e32 v28, v2
	v_mul_f32_e32 v2, 0xbfb8aa3b, v3
	v_exp_f32_e32 v29, v2
	ds_read_b128 v[14:17], v167
	ds_read_b128 v[10:13], v167 offset:16
	ds_read_b128 v[24:27], v167 offset:144
	v_lshlrev_b32_e32 v32, 16, v21
	v_and_b32_e32 v21, 0xffff0000, v21
	s_waitcnt lgkmcnt(2)
	v_and_b32_e32 v20, 0xffff0000, v14
	v_pk_add_f32 v[28:29], v[28:29], 1.0 op_sel_hi:[1,0]
	v_lshlrev_b32_e32 v14, 16, v14
	v_mul_f32_e32 v21, 0xbfb8aa3b, v21
	v_exp_f32_e32 v21, v21
	ds_read_b128 v[6:9], v167 offset:32
	ds_read_b128 v[2:5], v167 offset:48
	v_rcp_f32_e32 v30, v29
	s_nop 0
	v_mul_f32_e32 v29, v20, v30
	v_mul_f32_e32 v20, 0xbfb8aa3b, v32
	v_exp_f32_e32 v20, v20
	v_and_b32_e32 v32, 0xffff0000, v15
	v_pk_add_f32 v[20:21], v[20:21], 1.0 op_sel_hi:[1,0]
	v_rcp_f32_e32 v30, v28
	s_nop 0
	v_mul_f32_e32 v28, v14, v30
	v_lshlrev_b32_e32 v30, 16, v15
	v_rcp_f32_e32 v14, v21
	s_nop 0
	v_mul_f32_e32 v32, v32, v14
	v_lshlrev_b32_e32 v14, 16, v22
	v_and_b32_e32 v15, 0xffff0000, v22
	v_mul_f32_e32 v14, 0xbfb8aa3b, v14
	v_mul_f32_e32 v15, 0xbfb8aa3b, v15
	v_exp_f32_e32 v14, v14
	v_exp_f32_e32 v15, v15
	v_rcp_f32_e32 v21, v20
	s_nop 0
	v_mul_f32_e32 v22, v30, v21
	v_and_b32_e32 v20, 0xffff0000, v16
	v_pk_add_f32 v[14:15], v[14:15], 1.0 op_sel_hi:[1,0]
	v_lshlrev_b32_e32 v16, 16, v16
	v_lshlrev_b32_e32 v31, 16, v23
	v_and_b32_e32 v23, 0xffff0000, v23
	v_rcp_f32_e32 v21, v15
	s_nop 0
	v_mul_f32_e32 v30, v20, v21
	v_mul_f32_e32 v20, 0xbfb8aa3b, v31
	v_mul_f32_e32 v21, 0xbfb8aa3b, v23
	v_exp_f32_e32 v20, v20
	v_exp_f32_e32 v21, v21
	v_and_b32_e32 v23, 0xffff0000, v17
	v_pk_add_f32 v[20:21], v[20:21], 1.0 op_sel_hi:[1,0]
	v_rcp_f32_e32 v15, v14
	s_nop 0
	v_mul_f32_e32 v16, v16, v15
	v_lshlrev_b32_e32 v14, 16, v17
	v_rcp_f32_e32 v15, v21
	v_cvt_pk_bf16_f32 v16, v16, v30
	v_mul_f32_e32 v17, v23, v15
	v_rcp_f32_e32 v15, v20
	s_nop 0
	v_mul_f32_e32 v23, v14, v15
	s_waitcnt lgkmcnt(2)
	v_lshlrev_b32_e32 v20, 16, v24
	v_and_b32_e32 v21, 0xffff0000, v24
	v_mul_f32_e32 v20, 0xbfb8aa3b, v20
	v_mul_f32_e32 v21, 0xbfb8aa3b, v21
	v_exp_f32_e32 v20, v20
	v_exp_f32_e32 v21, v21
	v_cvt_pk_bf16_f32 v14, v28, v29
	v_cvt_pk_bf16_f32 v15, v22, v32
	v_cvt_pk_bf16_f32 v17, v23, v17
	global_store_dwordx4 v[18:19], v[14:17], off
	v_and_b32_e32 v22, 0xffff0000, v25
	s_nop 0
	v_and_b32_e32 v16, 0xffff0000, v10
	v_pk_add_f32 v[14:15], v[20:21], 1.0 op_sel_hi:[1,0]
	v_lshlrev_b32_e32 v21, 16, v25
	v_lshlrev_b32_e32 v10, 16, v10
	v_rcp_f32_e32 v17, v15
	s_nop 0
	v_mul_f32_e32 v20, v16, v17
	v_mul_f32_e32 v16, 0xbfb8aa3b, v21
	v_mul_f32_e32 v17, 0xbfb8aa3b, v22
	v_exp_f32_e32 v16, v16
	v_exp_f32_e32 v17, v17
	v_and_b32_e32 v21, 0xffff0000, v11
	v_pk_add_f32 v[16:17], v[16:17], 1.0 op_sel_hi:[1,0]
	v_rcp_f32_e32 v15, v14
	s_nop 0
	v_mul_f32_e32 v24, v10, v15
	v_lshlrev_b32_e32 v14, 16, v11
	v_rcp_f32_e32 v10, v17
	v_and_b32_e32 v23, 0xffff0000, v27
	v_mul_f32_e32 v17, v21, v10
	v_lshlrev_b32_e32 v10, 16, v26
	v_and_b32_e32 v11, 0xffff0000, v26
	v_mul_f32_e32 v10, 0xbfb8aa3b, v10
	v_mul_f32_e32 v11, 0xbfb8aa3b, v11
	v_exp_f32_e32 v10, v10
	v_exp_f32_e32 v11, v11
	v_rcp_f32_e32 v15, v16
	s_nop 0
	v_mul_f32_e32 v16, v14, v15
	v_and_b32_e32 v14, 0xffff0000, v12
	v_pk_add_f32 v[10:11], v[10:11], 1.0 op_sel_hi:[1,0]
	v_lshlrev_b32_e32 v22, 16, v27
	v_lshlrev_b32_e32 v12, 16, v12
	v_rcp_f32_e32 v15, v11
	s_nop 0
	v_mul_f32_e32 v21, v14, v15
	v_mul_f32_e32 v14, 0xbfb8aa3b, v22
	v_mul_f32_e32 v15, 0xbfb8aa3b, v23
	v_exp_f32_e32 v14, v14
	v_exp_f32_e32 v15, v15
	v_and_b32_e32 v22, 0xffff0000, v13
	v_pk_add_f32 v[14:15], v[14:15], 1.0 op_sel_hi:[1,0]
	v_rcp_f32_e32 v11, v10
	s_nop 0
	v_mul_f32_e32 v26, v12, v11
	v_lshlrev_b32_e32 v10, 16, v13
	v_rcp_f32_e32 v11, v15
	s_nop 0
	v_mul_f32_e32 v27, v22, v11
	v_rcp_f32_e32 v11, v14
	s_nop 0
	v_mul_f32_e32 v28, v10, v11
	ds_read_b128 v[10:13], v167 offset:160
	v_cvt_pk_bf16_f32 v15, v16, v17
	v_cvt_pk_bf16_f32 v14, v24, v20
	v_cvt_pk_bf16_f32 v16, v26, v21
	ds_read_b128 v[20:23], v167 offset:176
	s_waitcnt lgkmcnt(1)
; DI unsigned pk2(float a, float b) { fl2_t f = {a, b}; bf2_t r = __builtin_convertvector(f, bf2_t); return __builtin_bit_cast(unsigned, r); }
; DI void phase2(const Params& p, char* lds) {
;     ...
;       for (int q = 0; q < 4; ++q) {
;         float z[8];
; #pragma unroll
;         for (int u = 0; u < 2; ++u) {
;           float4 a = cs4(Cs, row, hf * 32 + q * 8 + u * 4);
;           float4 g = cs4(Cs, row, 64 + hf * 32 + q * 8 + u * 4);
;           z[u * 4 + 0] = a.x / (1.f + __expf(-g.x)); z[u * 4 + 1] = a.y / (1.f + __expf(-g.y));
;           z[u * 4 + 2] = a.z / (1.f + __expf(-g.z)); z[u * 4 + 3] = a.w / (1.f + __expf(-g.w));
;         }
;         u32x4 o; o[0] = pk2(z[0], z[1]); o[1] = pk2(z[2], z[3]); o[2] = pk2(z[4], z[5]); o[3] = pk2(z[6], z[7]);
;         *(u32x4*)(dst + q * 8) = o;
;       }
	v_lshlrev_b32_e32 v17, 16, v10
	v_and_b32_e32 v10, 0xffff0000, v10
	v_mul_f32_e32 v17, 0xbfb8aa3b, v17
	v_mul_f32_e32 v10, 0xbfb8aa3b, v10
	v_exp_f32_e32 v24, v17
	v_exp_f32_e32 v25, v10
	v_cvt_pk_bf16_f32 v17, v28, v27
	global_store_dwordx4 v[18:19], v[14:17], off offset:16
	v_and_b32_e32 v10, 0xffff0000, v6
	v_lshlrev_b32_e32 v6, 16, v6
	v_pk_add_f32 v[14:15], v[24:25], 1.0 op_sel_hi:[1,0]
	v_lshlrev_b32_e32 v24, 16, v11
	v_and_b32_e32 v11, 0xffff0000, v11
	v_mul_f32_e32 v11, 0xbfb8aa3b, v11
	v_exp_f32_e32 v11, v11
	v_rcp_f32_e32 v16, v15
	s_nop 0
	v_mul_f32_e32 v15, v10, v16
	v_mul_f32_e32 v10, 0xbfb8aa3b, v24
	v_exp_f32_e32 v10, v10
	v_and_b32_e32 v24, 0xffff0000, v7
	v_pk_add_f32 v[10:11], v[10:11], 1.0 op_sel_hi:[1,0]
	v_rcp_f32_e32 v16, v14
	s_nop 0
	v_mul_f32_e32 v14, v6, v16
	v_lshlrev_b32_e32 v16, 16, v7
	v_rcp_f32_e32 v6, v11
	s_nop 0
	v_mul_f32_e32 v24, v24, v6
	v_lshlrev_b32_e32 v6, 16, v12
	v_and_b32_e32 v7, 0xffff0000, v12
	v_mul_f32_e32 v6, 0xbfb8aa3b, v6
	v_mul_f32_e32 v7, 0xbfb8aa3b, v7
	v_exp_f32_e32 v6, v6
	v_exp_f32_e32 v7, v7
	v_rcp_f32_e32 v11, v10
	s_nop 0
	v_mul_f32_e32 v12, v16, v11
	v_and_b32_e32 v10, 0xffff0000, v8
	v_pk_add_f32 v[6:7], v[6:7], 1.0 op_sel_hi:[1,0]
	v_lshlrev_b32_e32 v8, 16, v8
	v_lshlrev_b32_e32 v17, 16, v13
	v_and_b32_e32 v13, 0xffff0000, v13
	v_rcp_f32_e32 v11, v7
	s_nop 0
	v_mul_f32_e32 v16, v10, v11
	v_mul_f32_e32 v10, 0xbfb8aa3b, v17
	v_mul_f32_e32 v11, 0xbfb8aa3b, v13
	v_exp_f32_e32 v10, v10
	v_exp_f32_e32 v11, v11
	v_and_b32_e32 v13, 0xffff0000, v9
	v_pk_add_f32 v[10:11], v[10:11], 1.0 op_sel_hi:[1,0]
	v_rcp_f32_e32 v7, v6
	s_nop 0
	v_mul_f32_e32 v8, v8, v7
	v_lshlrev_b32_e32 v6, 16, v9
	v_rcp_f32_e32 v7, v11
	v_cvt_pk_bf16_f32 v8, v8, v16
	v_mul_f32_e32 v9, v13, v7
	v_rcp_f32_e32 v7, v10
	s_nop 0
	v_mul_f32_e32 v13, v6, v7
	s_waitcnt lgkmcnt(0)
	v_lshlrev_b32_e32 v10, 16, v20
	v_and_b32_e32 v11, 0xffff0000, v20
	v_mul_f32_e32 v10, 0xbfb8aa3b, v10
	v_mul_f32_e32 v11, 0xbfb8aa3b, v11
	v_exp_f32_e32 v10, v10
	v_exp_f32_e32 v11, v11
	v_cvt_pk_bf16_f32 v6, v14, v15
	v_cvt_pk_bf16_f32 v7, v12, v24
	v_cvt_pk_bf16_f32 v9, v13, v9
	global_store_dwordx4 v[18:19], v[6:9], off offset:32
	v_and_b32_e32 v12, 0xffff0000, v21
	s_nop 0
	v_and_b32_e32 v8, 0xffff0000, v2
	v_pk_add_f32 v[6:7], v[10:11], 1.0 op_sel_hi:[1,0]
	v_lshlrev_b32_e32 v2, 16, v2
	v_lshlrev_b32_e32 v11, 16, v21
	v_rcp_f32_e32 v9, v7
	s_nop 0
	v_mul_f32_e32 v10, v8, v9
	v_mul_f32_e32 v8, 0xbfb8aa3b, v11
	v_mul_f32_e32 v9, 0xbfb8aa3b, v12
	v_exp_f32_e32 v8, v8
	v_exp_f32_e32 v9, v9
	v_and_b32_e32 v11, 0xffff0000, v3
	v_pk_add_f32 v[8:9], v[8:9], 1.0 op_sel_hi:[1,0]
	v_rcp_f32_e32 v7, v6
	s_nop 0
	v_mul_f32_e32 v14, v2, v7
	v_lshlrev_b32_e32 v6, 16, v3
	v_rcp_f32_e32 v2, v9
	v_and_b32_e32 v13, 0xffff0000, v23
	v_mul_f32_e32 v9, v11, v2
	v_lshlrev_b32_e32 v2, 16, v22
	v_and_b32_e32 v3, 0xffff0000, v22
	v_mul_f32_e32 v2, 0xbfb8aa3b, v2
	v_mul_f32_e32 v3, 0xbfb8aa3b, v3
	v_exp_f32_e32 v2, v2
	v_exp_f32_e32 v3, v3
	v_rcp_f32_e32 v7, v8
	s_nop 0
	v_mul_f32_e32 v8, v6, v7
	v_and_b32_e32 v6, 0xffff0000, v4
	v_pk_add_f32 v[2:3], v[2:3], 1.0 op_sel_hi:[1,0]
	v_lshlrev_b32_e32 v4, 16, v4
	v_lshlrev_b32_e32 v12, 16, v23
	v_rcp_f32_e32 v7, v3
	s_nop 0
	v_mul_f32_e32 v11, v6, v7
	v_mul_f32_e32 v6, 0xbfb8aa3b, v12
	v_mul_f32_e32 v7, 0xbfb8aa3b, v13
	v_exp_f32_e32 v6, v6
	v_exp_f32_e32 v7, v7
	v_and_b32_e32 v12, 0xffff0000, v5
	v_pk_add_f32 v[6:7], v[6:7], 1.0 op_sel_hi:[1,0]
	v_rcp_f32_e32 v3, v2
	s_nop 0
	v_mul_f32_e32 v4, v4, v3
	v_lshlrev_b32_e32 v2, 16, v5
	v_rcp_f32_e32 v3, v7
	v_cvt_pk_bf16_f32 v4, v4, v11
	v_mul_f32_e32 v5, v12, v3
	v_rcp_f32_e32 v3, v6
	s_nop 0
	v_mul_f32_e32 v6, v2, v3
	v_cvt_pk_bf16_f32 v2, v14, v10
	v_cvt_pk_bf16_f32 v3, v8, v9
	v_cvt_pk_bf16_f32 v5, v6, v5
	global_store_dwordx4 v[18:19], v[2:5], off offset:48
	s_mov_b64 s[26:27], 0

; DI unsigned pk2(float a, float b) { fl2_t f = {a, b}; bf2_t r = __builtin_convertvector(f, bf2_t); return __builtin_bit_cast(unsigned, r); }
; DI void phase2(const Params& p, char* lds) {
;     ...
;       const int j = nt - 12, row = tid & 127, hf = tid >> 7;
;       bfr* dst = (bfr*)(ws + WS_Z) + (size_t)(t0h + row) * 512 + j * 64 + hf * 32;
; #pragma unroll
;       for (int q = 0; q < 4; ++q) {
;         float z[8];
; #pragma unroll
;         for (int u = 0; u < 2; ++u) {
;           float4 a = cs4(Cs, row, hf * 32 + q * 8 + u * 4);
;           float4 g = cs4(Cs, row, 64 + hf * 32 + q * 8 + u * 4);
;           z[u * 4 + 0] = a.x / (1.f + __expf(-g.x)); z[u * 4 + 1] = a.y / (1.f + __expf(-g.y));
;           z[u * 4 + 2] = a.z / (1.f + __expf(-g.z)); z[u * 4 + 3] = a.w / (1.f + __expf(-g.w));
;         }
;         u32x4 o; o[0] = pk2(z[0], z[1]); o[1] = pk2(z[2], z[3]); o[2] = pk2(z[4], z[5]); o[3] = pk2(z[6], z[7]);
;         *(u32x4*)(dst + q * 8) = o;
;       }
.LBB0_131:
	s_cmp_gt_u32 s3, 11
	s_cbranch_scc0 .LBB0_133
	v_add_u32_e32 v2, s44, v166
	ds_read_b128 v[20:23], v167 offset:384
	v_ashrrev_i32_e32 v3, 31, v2
	v_lshlrev_b64 v[2:3], 10, v[2:3]
	s_lshl_b32 s8, s45, 6
	v_lshl_add_u64 v[2:3], s[14:15], 0, v[2:3]
	s_addk_i32 s8, 0xfd00
	v_lshl_add_u64 v[2:3], s[8:9], 1, v[2:3]
	v_lshlrev_b32_e32 v4, 1, v156
	v_mov_b32_e32 v5, v151
	v_lshl_add_u64 v[18:19], v[2:3], 0, v[4:5]
	s_waitcnt lgkmcnt(0)
	v_lshlrev_b32_e32 v2, 16, v20
	v_and_b32_e32 v3, 0xffff0000, v20
	v_mul_f32_e32 v2, 0xbfb8aa3b, v2
	v_exp_f32_e32 v28, v2
	v_mul_f32_e32 v2, 0xbfb8aa3b, v3
	v_exp_f32_e32 v29, v2
	ds_read_b128 v[14:17], v167 offset:256
	ds_read_b128 v[10:13], v167 offset:272
	ds_read_b128 v[24:27], v167 offset:400
	v_lshlrev_b32_e32 v32, 16, v21
	v_and_b32_e32 v21, 0xffff0000, v21
	s_waitcnt lgkmcnt(2)
	v_and_b32_e32 v20, 0xffff0000, v14
	v_pk_add_f32 v[28:29], v[28:29], 1.0 op_sel_hi:[1,0]
	v_lshlrev_b32_e32 v14, 16, v14
	v_mul_f32_e32 v21, 0xbfb8aa3b, v21
	v_exp_f32_e32 v21, v21
	ds_read_b128 v[6:9], v167 offset:288
	ds_read_b128 v[2:5], v167 offset:304
	v_rcp_f32_e32 v30, v29
	s_nop 0
	v_mul_f32_e32 v29, v20, v30
	v_mul_f32_e32 v20, 0xbfb8aa3b, v32
	v_exp_f32_e32 v20, v20
	v_and_b32_e32 v32, 0xffff0000, v15
	v_pk_add_f32 v[20:21], v[20:21], 1.0 op_sel_hi:[1,0]
	v_rcp_f32_e32 v30, v28
	s_nop 0
	v_mul_f32_e32 v28, v14, v30
	v_lshlrev_b32_e32 v30, 16, v15
	v_rcp_f32_e32 v14, v21
	s_nop 0
	v_mul_f32_e32 v32, v32, v14
	v_lshlrev_b32_e32 v14, 16, v22
	v_and_b32_e32 v15, 0xffff0000, v22
	v_mul_f32_e32 v14, 0xbfb8aa3b, v14
	v_mul_f32_e32 v15, 0xbfb8aa3b, v15
	v_exp_f32_e32 v14, v14
	v_exp_f32_e32 v15, v15
	v_rcp_f32_e32 v21, v20
	s_nop 0
	v_mul_f32_e32 v22, v30, v21
	v_and_b32_e32 v20, 0xffff0000, v16
	v_pk_add_f32 v[14:15], v[14:15], 1.0 op_sel_hi:[1,0]
	v_lshlrev_b32_e32 v16, 16, v16
	v_lshlrev_b32_e32 v31, 16, v23
	v_and_b32_e32 v23, 0xffff0000, v23
	v_rcp_f32_e32 v21, v15
	s_nop 0
	v_mul_f32_e32 v30, v20, v21
	v_mul_f32_e32 v20, 0xbfb8aa3b, v31
	v_mul_f32_e32 v21, 0xbfb8aa3b, v23
	v_exp_f32_e32 v20, v20
	v_exp_f32_e32 v21, v21
	v_and_b32_e32 v23, 0xffff0000, v17
	v_pk_add_f32 v[20:21], v[20:21], 1.0 op_sel_hi:[1,0]
	v_rcp_f32_e32 v15, v14
	s_nop 0
	v_mul_f32_e32 v16, v16, v15
	v_lshlrev_b32_e32 v14, 16, v17
	v_rcp_f32_e32 v15, v21
	v_cvt_pk_bf16_f32 v16, v16, v30
	v_mul_f32_e32 v17, v23, v15
	v_rcp_f32_e32 v15, v20
	s_nop 0
	v_mul_f32_e32 v23, v14, v15
	s_waitcnt lgkmcnt(2)
	v_lshlrev_b32_e32 v20, 16, v24
	v_and_b32_e32 v21, 0xffff0000, v24
	v_mul_f32_e32 v20, 0xbfb8aa3b, v20
	v_mul_f32_e32 v21, 0xbfb8aa3b, v21
	v_exp_f32_e32 v20, v20
	v_exp_f32_e32 v21, v21
	v_cvt_pk_bf16_f32 v14, v28, v29
	v_cvt_pk_bf16_f32 v15, v22, v32
	v_cvt_pk_bf16_f32 v17, v23, v17
	global_store_dwordx4 v[18:19], v[14:17], off
	v_and_b32_e32 v22, 0xffff0000, v25
	s_nop 0
	v_and_b32_e32 v16, 0xffff0000, v10
	v_pk_add_f32 v[14:15], v[20:21], 1.0 op_sel_hi:[1,0]
	v_lshlrev_b32_e32 v21, 16, v25
	v_lshlrev_b32_e32 v10, 16, v10
	v_rcp_f32_e32 v17, v15
	s_nop 0
	v_mul_f32_e32 v20, v16, v17
	v_mul_f32_e32 v16, 0xbfb8aa3b, v21
	v_mul_f32_e32 v17, 0xbfb8aa3b, v22
	v_exp_f32_e32 v16, v16
	v_exp_f32_e32 v17, v17
	v_and_b32_e32 v21, 0xffff0000, v11
	v_pk_add_f32 v[16:17], v[16:17], 1.0 op_sel_hi:[1,0]
	v_rcp_f32_e32 v15, v14
	s_nop 0
	v_mul_f32_e32 v24, v10, v15
	v_lshlrev_b32_e32 v14, 16, v11
	v_rcp_f32_e32 v10, v17
	v_and_b32_e32 v23, 0xffff0000, v27
	v_mul_f32_e32 v17, v21, v10
	v_lshlrev_b32_e32 v10, 16, v26
	v_and_b32_e32 v11, 0xffff0000, v26
	v_mul_f32_e32 v10, 0xbfb8aa3b, v10
	v_mul_f32_e32 v11, 0xbfb8aa3b, v11
	v_exp_f32_e32 v10, v10
	v_exp_f32_e32 v11, v11
	v_rcp_f32_e32 v15, v16
	s_nop 0
	v_mul_f32_e32 v16, v14, v15
	v_and_b32_e32 v14, 0xffff0000, v12
	v_pk_add_f32 v[10:11], v[10:11], 1.0 op_sel_hi:[1,0]
	v_lshlrev_b32_e32 v22, 16, v27
	v_lshlrev_b32_e32 v12, 16, v12
	v_rcp_f32_e32 v15, v11
	s_nop 0
	v_mul_f32_e32 v21, v14, v15
	v_mul_f32_e32 v14, 0xbfb8aa3b, v22
	v_mul_f32_e32 v15, 0xbfb8aa3b, v23
	v_exp_f32_e32 v14, v14
	v_exp_f32_e32 v15, v15
	v_and_b32_e32 v22, 0xffff0000, v13
	v_pk_add_f32 v[14:15], v[14:15], 1.0 op_sel_hi:[1,0]
	v_rcp_f32_e32 v11, v10
	s_nop 0
	v_mul_f32_e32 v26, v12, v11
	v_lshlrev_b32_e32 v10, 16, v13
	v_rcp_f32_e32 v11, v15
	s_nop 0
	v_mul_f32_e32 v27, v22, v11
	v_rcp_f32_e32 v11, v14
	s_nop 0
	v_mul_f32_e32 v28, v10, v11
	ds_read_b128 v[10:13], v167 offset:416
	v_cvt_pk_bf16_f32 v15, v16, v17
	v_cvt_pk_bf16_f32 v14, v24, v20
	v_cvt_pk_bf16_f32 v16, v26, v21
	ds_read_b128 v[20:23], v167 offset:432
	s_waitcnt lgkmcnt(1)
; DI unsigned pk2(float a, float b) { fl2_t f = {a, b}; bf2_t r = __builtin_convertvector(f, bf2_t); return __builtin_bit_cast(unsigned, r); }
; DI void phase2(const Params& p, char* lds) {
;     ...
;       for (int q = 0; q < 4; ++q) {
;         float z[8];
; #pragma unroll
;         for (int u = 0; u < 2; ++u) {
;           float4 a = cs4(Cs, row, hf * 32 + q * 8 + u * 4);
;           float4 g = cs4(Cs, row, 64 + hf * 32 + q * 8 + u * 4);
;           z[u * 4 + 0] = a.x / (1.f + __expf(-g.x)); z[u * 4 + 1] = a.y / (1.f + __expf(-g.y));
;           z[u * 4 + 2] = a.z / (1.f + __expf(-g.z)); z[u * 4 + 3] = a.w / (1.f + __expf(-g.w));
;         }
;         u32x4 o; o[0] = pk2(z[0], z[1]); o[1] = pk2(z[2], z[3]); o[2] = pk2(z[4], z[5]); o[3] = pk2(z[6], z[7]);
;         *(u32x4*)(dst + q * 8) = o;
;       }
	v_lshlrev_b32_e32 v17, 16, v10
	v_and_b32_e32 v10, 0xffff0000, v10
	v_mul_f32_e32 v17, 0xbfb8aa3b, v17
	v_mul_f32_e32 v10, 0xbfb8aa3b, v10
	v_exp_f32_e32 v24, v17
	v_exp_f32_e32 v25, v10
	v_cvt_pk_bf16_f32 v17, v28, v27
	global_store_dwordx4 v[18:19], v[14:17], off offset:16
	v_and_b32_e32 v10, 0xffff0000, v6
	v_lshlrev_b32_e32 v6, 16, v6
	v_pk_add_f32 v[14:15], v[24:25], 1.0 op_sel_hi:[1,0]
	v_lshlrev_b32_e32 v24, 16, v11
	v_and_b32_e32 v11, 0xffff0000, v11
	v_mul_f32_e32 v11, 0xbfb8aa3b, v11
	v_exp_f32_e32 v11, v11
	v_rcp_f32_e32 v16, v15
	s_nop 0
	v_mul_f32_e32 v15, v10, v16
	v_mul_f32_e32 v10, 0xbfb8aa3b, v24
	v_exp_f32_e32 v10, v10
	v_and_b32_e32 v24, 0xffff0000, v7
	v_pk_add_f32 v[10:11], v[10:11], 1.0 op_sel_hi:[1,0]
	v_rcp_f32_e32 v16, v14
	s_nop 0
	v_mul_f32_e32 v14, v6, v16
	v_lshlrev_b32_e32 v16, 16, v7
	v_rcp_f32_e32 v6, v11
	s_nop 0
	v_mul_f32_e32 v24, v24, v6
	v_lshlrev_b32_e32 v6, 16, v12
	v_and_b32_e32 v7, 0xffff0000, v12
	v_mul_f32_e32 v6, 0xbfb8aa3b, v6
	v_mul_f32_e32 v7, 0xbfb8aa3b, v7
	v_exp_f32_e32 v6, v6
	v_exp_f32_e32 v7, v7
	v_rcp_f32_e32 v11, v10
	s_nop 0
	v_mul_f32_e32 v12, v16, v11
	v_and_b32_e32 v10, 0xffff0000, v8
	v_pk_add_f32 v[6:7], v[6:7], 1.0 op_sel_hi:[1,0]
	v_lshlrev_b32_e32 v8, 16, v8
	v_lshlrev_b32_e32 v17, 16, v13
	v_and_b32_e32 v13, 0xffff0000, v13
	v_rcp_f32_e32 v11, v7
	s_nop 0
	v_mul_f32_e32 v16, v10, v11
	v_mul_f32_e32 v10, 0xbfb8aa3b, v17
	v_mul_f32_e32 v11, 0xbfb8aa3b, v13
	v_exp_f32_e32 v10, v10
	v_exp_f32_e32 v11, v11
	v_and_b32_e32 v13, 0xffff0000, v9
	v_pk_add_f32 v[10:11], v[10:11], 1.0 op_sel_hi:[1,0]
	v_rcp_f32_e32 v7, v6
	s_nop 0
	v_mul_f32_e32 v8, v8, v7
	v_lshlrev_b32_e32 v6, 16, v9
	v_rcp_f32_e32 v7, v11
	v_cvt_pk_bf16_f32 v8, v8, v16
	v_mul_f32_e32 v9, v13, v7
	v_rcp_f32_e32 v7, v10
	s_nop 0
	v_mul_f32_e32 v13, v6, v7
	s_waitcnt lgkmcnt(0)
	v_lshlrev_b32_e32 v10, 16, v20
	v_and_b32_e32 v11, 0xffff0000, v20
	v_mul_f32_e32 v10, 0xbfb8aa3b, v10
	v_mul_f32_e32 v11, 0xbfb8aa3b, v11
	v_exp_f32_e32 v10, v10
	v_exp_f32_e32 v11, v11
	v_cvt_pk_bf16_f32 v6, v14, v15
	v_cvt_pk_bf16_f32 v7, v12, v24
	v_cvt_pk_bf16_f32 v9, v13, v9
	global_store_dwordx4 v[18:19], v[6:9], off offset:32
	v_and_b32_e32 v12, 0xffff0000, v21
	s_nop 0
	v_and_b32_e32 v8, 0xffff0000, v2
	v_pk_add_f32 v[6:7], v[10:11], 1.0 op_sel_hi:[1,0]
	v_lshlrev_b32_e32 v2, 16, v2
	v_lshlrev_b32_e32 v11, 16, v21
	v_rcp_f32_e32 v9, v7
	s_nop 0
	v_mul_f32_e32 v10, v8, v9
	v_mul_f32_e32 v8, 0xbfb8aa3b, v11
	v_mul_f32_e32 v9, 0xbfb8aa3b, v12
	v_exp_f32_e32 v8, v8
	v_exp_f32_e32 v9, v9
	v_and_b32_e32 v11, 0xffff0000, v3
	v_pk_add_f32 v[8:9], v[8:9], 1.0 op_sel_hi:[1,0]
	v_rcp_f32_e32 v7, v6
	s_nop 0
	v_mul_f32_e32 v14, v2, v7
	v_lshlrev_b32_e32 v6, 16, v3
	v_rcp_f32_e32 v2, v9
	v_and_b32_e32 v13, 0xffff0000, v23
	v_mul_f32_e32 v9, v11, v2
	v_lshlrev_b32_e32 v2, 16, v22
	v_and_b32_e32 v3, 0xffff0000, v22
	v_mul_f32_e32 v2, 0xbfb8aa3b, v2
	v_mul_f32_e32 v3, 0xbfb8aa3b, v3
	v_exp_f32_e32 v2, v2
	v_exp_f32_e32 v3, v3
	v_rcp_f32_e32 v7, v8
	s_nop 0
	v_mul_f32_e32 v8, v6, v7
	v_and_b32_e32 v6, 0xffff0000, v4
	v_pk_add_f32 v[2:3], v[2:3], 1.0 op_sel_hi:[1,0]
	v_lshlrev_b32_e32 v4, 16, v4
	v_lshlrev_b32_e32 v12, 16, v23
	v_rcp_f32_e32 v7, v3
	s_nop 0
	v_mul_f32_e32 v11, v6, v7
	v_mul_f32_e32 v6, 0xbfb8aa3b, v12
	v_mul_f32_e32 v7, 0xbfb8aa3b, v13
	v_exp_f32_e32 v6, v6
	v_exp_f32_e32 v7, v7
	v_and_b32_e32 v12, 0xffff0000, v5
	v_pk_add_f32 v[6:7], v[6:7], 1.0 op_sel_hi:[1,0]
	v_rcp_f32_e32 v3, v2
	s_nop 0
	v_mul_f32_e32 v4, v4, v3
	v_lshlrev_b32_e32 v2, 16, v5
	v_rcp_f32_e32 v3, v7
	v_cvt_pk_bf16_f32 v4, v4, v11
	v_mul_f32_e32 v5, v12, v3
	v_rcp_f32_e32 v3, v6
	s_nop 0
	v_mul_f32_e32 v6, v2, v3
	v_cvt_pk_bf16_f32 v2, v14, v10
	v_cvt_pk_bf16_f32 v3, v8, v9
	v_cvt_pk_bf16_f32 v5, v6, v5
	global_store_dwordx4 v[18:19], v[2:5], off offset:48
	s_mov_b64 s[26:27], 0

; DI unsigned pk2(float a, float b) { fl2_t f = {a, b}; bf2_t r = __builtin_convertvector(f, bf2_t); return __builtin_bit_cast(unsigned, r); }
; DI void conv_item(const Params& p, char* lds, int t0, int tid) {
;     ...
; #pragma unroll
;     for (int i = 0; i < 8; ++i) {
;       const float s1 = red[(0 * 8 + i) * 2] + red[(1 * 8 + i) * 2] + red[(2 * 8 + i) * 2] + red[(3 * 8 + i) * 2];
;       const float s2 = red[(0 * 8 + i) * 2 + 1] + red[(1 * 8 + i) * 2 + 1] + red[(2 * 8 + i) * 2 + 1] + red[(3 * 8 + i) * 2 + 1];
;       const float mu = s1 * (1.f / 512.f);
;       const float var = fmaxf(s2 * (1.f / 512.f) - mu * mu, 0.f);
;       const float rstd = rsqrtf(var + 1e-6f);
;       float a = (ya[i] - mu) * rstd * gl.x + bl.x, b = (yb[i] - mu) * rstd * gl.y + bl.y;
;       a = a / (1.f + __expf(-a)); b = b / (1.f + __expf(-b));
;       Hu[((size_t)(t0 + ps * 8 + i) * D + 512) / 2 + tid] = pk2(a, b);
;     }
.LBB0_195:
	s_or_b64 exec, exec, s[6:7]
	s_waitcnt lgkmcnt(0)
	s_barrier
	ds_read_b128 v[160:163], v220 offset:63552
	ds_read_b128 v[166:169], v220 offset:63488
	ds_read_b128 v[6:9], v220 offset:63504
	ds_read_b128 v[170:173], v220 offset:63616
	ds_read_b128 v[174:177], v220 offset:63680
	ds_read_b128 v[178:181], v220 offset:63568
	s_waitcnt lgkmcnt(4)
	v_pk_add_f32 v[4:5], v[166:167], v[160:161]
	v_pk_add_f32 v[162:163], v[168:169], v[162:163]
	s_waitcnt lgkmcnt(2)
	v_pk_add_f32 v[4:5], v[4:5], v[170:171]
	v_pk_add_f32 v[162:163], v[162:163], v[172:173]
	s_waitcnt lgkmcnt(1)
	v_pk_add_f32 v[4:5], v[4:5], v[174:175]
	v_pk_add_f32 v[162:163], v[162:163], v[176:177]
	v_pk_mul_f32 v[4:5], v[4:5], s[0:1] op_sel_hi:[1,0]
	v_pk_mul_f32 v[162:163], v[162:163], s[0:1] op_sel_hi:[1,0]
	v_fma_f32 v160, -v4, v4, v5
	v_max_f32_e32 v160, 0, v160
	v_add_f32_e32 v160, 0x358637bd, v160
	v_pk_add_f32 v[2:3], v[2:3], v[4:5] op_sel_hi:[1,0] neg_lo:[0,1] neg_hi:[0,1]
	v_fma_f32 v168, -v162, v162, v163
	v_rsq_f32_e32 v160, v160
	v_max_f32_e32 v168, 0, v168
	v_add_f32_e32 v168, 0x358637bd, v168
	v_pk_mul_f32 v[2:3], v[2:3], v[160:161] op_sel_hi:[1,0]
	v_pk_add_f32 v[156:157], v[156:157], v[162:163] op_sel_hi:[1,0] neg_lo:[0,1] neg_hi:[0,1]
	v_pk_fma_f32 v[166:167], v[144:145], v[2:3], v[146:147]
	v_add_u32_e32 v160, s8, v1
	v_mul_f32_e32 v2, 0xbfb8aa3b, v166
	v_mul_f32_e32 v3, 0xbfb8aa3b, v167
	v_exp_f32_e32 v2, v2
	v_exp_f32_e32 v3, v3
	ds_read_b128 v[182:185], v220 offset:63632
	ds_read_b128 v[186:189], v220 offset:63696
	s_waitcnt lgkmcnt(2)
	v_pk_add_f32 v[6:7], v[6:7], v[178:179]
	v_pk_add_f32 v[170:171], v[2:3], 1.0 op_sel_hi:[1,0]
	v_pk_add_f32 v[8:9], v[8:9], v[180:181]
	s_waitcnt lgkmcnt(1)
	v_pk_add_f32 v[6:7], v[6:7], v[182:183]
	v_pk_add_f32 v[8:9], v[8:9], v[184:185]
	s_waitcnt lgkmcnt(0)
	v_pk_add_f32 v[6:7], v[6:7], v[186:187]
	v_rcp_f32_e32 v161, v171
	v_rsq_f32_e32 v168, v168
	v_mul_f32_e32 v161, v167, v161
	v_rcp_f32_e32 v167, v170
	s_nop 0
	v_mul_f32_e32 v167, v166, v167
	v_mov_b32_e32 v166, v168
	v_pk_mul_f32 v[156:157], v[156:157], v[166:167] op_sel_hi:[1,0]
	v_cvt_pk_bf16_f32 v168, v167, v161
	v_pk_fma_f32 v[156:157], v[144:145], v[156:157], v[146:147]
	v_ashrrev_i32_e32 v161, 31, v160
	v_mul_f32_e32 v162, 0xbfb8aa3b, v156
	v_mul_f32_e32 v163, 0xbfb8aa3b, v157
	v_exp_f32_e32 v162, v162
	v_exp_f32_e32 v163, v163
	v_lshlrev_b64 v[166:167], 11, v[160:161]
	v_and_b32_e32 v166, 0xffffc000, v166
	v_lshl_add_u64 v[166:167], v[78:79], 0, v[166:167]
	v_pk_add_f32 v[162:163], v[162:163], 1.0 op_sel_hi:[1,0]
	global_store_dword v[166:167], v168, off
	v_pk_mul_f32 v[6:7], v[6:7], s[0:1] op_sel_hi:[1,0]
	v_pk_add_f32 v[8:9], v[8:9], v[188:189]
	ds_read_b128 v[2:5], v220 offset:63520
	v_rcp_f32_e32 v161, v163
	v_pk_mul_f32 v[8:9], v[8:9], s[0:1] op_sel_hi:[1,0]
	v_mul_f32_e32 v161, v157, v161
	v_fma_f32 v166, -v6, v6, v7
	v_max_f32_e32 v166, 0, v166
	v_add_f32_e32 v166, 0x358637bd, v166
	v_rcp_f32_e32 v157, v162
	v_rsq_f32_e32 v166, v166
	v_mul_f32_e32 v162, v156, v157
	v_pk_add_f32 v[6:7], v[158:159], v[6:7] op_sel_hi:[1,0] neg_lo:[0,1] neg_hi:[0,1]
	v_cvt_pk_bf16_f32 v161, v162, v161
	v_add_u32_e32 v158, 1, v160
	v_mov_b32_e32 v156, v166
	v_pk_mul_f32 v[6:7], v[6:7], v[156:157] op_sel_hi:[1,0]
	v_ashrrev_i32_e32 v159, 31, v158
	v_pk_fma_f32 v[6:7], v[144:145], v[6:7], v[146:147]
	v_lshlrev_b64 v[158:159], 11, v[158:159]
	v_mul_f32_e32 v156, 0xbfb8aa3b, v6
	v_mul_f32_e32 v157, 0xbfb8aa3b, v7
	v_exp_f32_e32 v156, v156
	v_exp_f32_e32 v157, v157
	v_lshl_add_u64 v[158:159], v[78:79], 0, v[158:159]
	global_store_dword v[158:159], v161, off
	s_add_i32 s8, s8, 8
	v_pk_add_f32 v[156:157], v[156:157], 1.0 op_sel_hi:[1,0]
	v_add_u32_e32 v238, 0x2000, v238
	s_cmp_lg_u32 s8, 32
	v_rcp_f32_e32 v158, v157
	v_fma_f32 v159, -v8, v8, v9
	v_mul_f32_e32 v157, v7, v158
	v_max_f32_e32 v159, 0, v159
	v_add_f32_e32 v159, 0x358637bd, v159
	v_rcp_f32_e32 v7, v156
	v_rsq_f32_e32 v159, v159
	v_mul_f32_e32 v156, v6, v7
	v_pk_add_f32 v[8:9], v[164:165], v[8:9] op_sel_hi:[1,0] neg_lo:[0,1] neg_hi:[0,1]
	v_cvt_pk_bf16_f32 v156, v156, v157
	v_mov_b32_e32 v6, v159
	v_pk_mul_f32 v[6:7], v[8:9], v[6:7] op_sel_hi:[1,0]
	v_add_u32_e32 v8, 2, v160
	v_pk_fma_f32 v[182:183], v[144:145], v[6:7], v[146:147]
	v_ashrrev_i32_e32 v9, 31, v8
	v_mul_f32_e32 v6, 0xbfb8aa3b, v182
	v_mul_f32_e32 v7, 0xbfb8aa3b, v183
	v_exp_f32_e32 v6, v6
	v_exp_f32_e32 v7, v7
	s_nop 0
	v_pk_add_f32 v[184:185], v[6:7], 1.0 op_sel_hi:[1,0]
	s_nop 0
	v_lshlrev_b64 v[6:7], 11, v[8:9]
	v_lshl_add_u64 v[6:7], v[78:79], 0, v[6:7]
	global_store_dword v[6:7], v156, off
	v_rcp_f32_e32 v6, v185
	s_nop 0
	v_mul_f32_e32 v183, v183, v6
	ds_read_b128 v[6:9], v220 offset:63584
	ds_read_b128 v[156:159], v220 offset:63648
	ds_read_b128 v[162:165], v220 offset:63712
	ds_read_b128 v[166:169], v220 offset:63536
	ds_read_b128 v[170:173], v220 offset:63600
	s_waitcnt lgkmcnt(4)
; DI unsigned pk2(float a, float b) { fl2_t f = {a, b}; bf2_t r = __builtin_convertvector(f, bf2_t); return __builtin_bit_cast(unsigned, r); }
; DI void conv_item(const Params& p, char* lds, int t0, int tid) {
;     ...
; #pragma unroll
;     for (int i = 0; i < 8; ++i) {
;       const float s1 = red[(0 * 8 + i) * 2] + red[(1 * 8 + i) * 2] + red[(2 * 8 + i) * 2] + red[(3 * 8 + i) * 2];
;       const float s2 = red[(0 * 8 + i) * 2 + 1] + red[(1 * 8 + i) * 2 + 1] + red[(2 * 8 + i) * 2 + 1] + red[(3 * 8 + i) * 2 + 1];
;       const float mu = s1 * (1.f / 512.f);
;       const float var = fmaxf(s2 * (1.f / 512.f) - mu * mu, 0.f);
;       const float rstd = rsqrtf(var + 1e-6f);
;       float a = (ya[i] - mu) * rstd * gl.x + bl.x, b = (yb[i] - mu) * rstd * gl.y + bl.y;
;       a = a / (1.f + __expf(-a)); b = b / (1.f + __expf(-b));
;       Hu[((size_t)(t0 + ps * 8 + i) * D + 512) / 2 + tid] = pk2(a, b);
;     }
	v_pk_add_f32 v[2:3], v[2:3], v[6:7]
	v_pk_add_f32 v[4:5], v[4:5], v[8:9]
	s_waitcnt lgkmcnt(3)
	v_pk_add_f32 v[2:3], v[2:3], v[156:157]
	v_pk_add_f32 v[4:5], v[4:5], v[158:159]
	s_waitcnt lgkmcnt(2)
	v_pk_add_f32 v[2:3], v[2:3], v[162:163]
	v_pk_add_f32 v[4:5], v[4:5], v[164:165]
	v_pk_mul_f32 v[2:3], v[2:3], s[0:1] op_sel_hi:[1,0]
	v_pk_mul_f32 v[4:5], v[4:5], s[0:1] op_sel_hi:[1,0]
	v_fma_f32 v6, -v2, v2, v3
	v_max_f32_e32 v6, 0, v6
	v_add_f32_e32 v6, 0x358637bd, v6
	v_pk_add_f32 v[2:3], v[148:149], v[2:3] op_sel_hi:[1,0] neg_lo:[0,1] neg_hi:[0,1]
	v_add_u32_e32 v148, 3, v160
	v_rsq_f32_e32 v6, v6
	v_rcp_f32_e32 v7, v184
	v_ashrrev_i32_e32 v149, 31, v148
	v_mul_f32_e32 v156, v182, v7
	v_pk_mul_f32 v[2:3], v[2:3], v[6:7] op_sel_hi:[1,0]
	v_lshlrev_b64 v[148:149], 11, v[148:149]
	v_pk_fma_f32 v[2:3], v[144:145], v[2:3], v[146:147]
	v_cvt_pk_bf16_f32 v156, v156, v183
	v_mul_f32_e32 v6, 0xbfb8aa3b, v2
	v_mul_f32_e32 v7, 0xbfb8aa3b, v3
	v_exp_f32_e32 v6, v6
	v_exp_f32_e32 v7, v7
	v_lshl_add_u64 v[148:149], v[78:79], 0, v[148:149]
	global_store_dword v[148:149], v156, off
	v_fma_f32 v8, -v4, v4, v5
	v_pk_add_f32 v[6:7], v[6:7], 1.0 op_sel_hi:[1,0]
	v_max_f32_e32 v8, 0, v8
	v_add_f32_e32 v8, 0x358637bd, v8
	v_pk_add_f32 v[4:5], v[150:151], v[4:5] op_sel_hi:[1,0] neg_lo:[0,1] neg_hi:[0,1]
	v_rcp_f32_e32 v148, v7
	v_rsq_f32_e32 v8, v8
	v_mul_f32_e32 v7, v3, v148
	v_rcp_f32_e32 v3, v6
	s_nop 0
	v_mul_f32_e32 v6, v2, v3
	v_mov_b32_e32 v2, v8
	v_pk_mul_f32 v[2:3], v[4:5], v[2:3] op_sel_hi:[1,0]
	v_cvt_pk_bf16_f32 v8, v6, v7
	v_pk_fma_f32 v[2:3], v[144:145], v[2:3], v[146:147]
	v_add_u32_e32 v6, 4, v160
	v_mul_f32_e32 v4, 0xbfb8aa3b, v2
	v_mul_f32_e32 v5, 0xbfb8aa3b, v3
	v_exp_f32_e32 v4, v4
	v_exp_f32_e32 v5, v5
	v_ashrrev_i32_e32 v7, 31, v6
	v_lshlrev_b64 v[6:7], 11, v[6:7]
	v_lshl_add_u64 v[6:7], v[78:79], 0, v[6:7]
	v_pk_add_f32 v[4:5], v[4:5], 1.0 op_sel_hi:[1,0]
	global_store_dword v[6:7], v8, off
	ds_read_b128 v[174:177], v220 offset:63664
	ds_read_b128 v[178:181], v220 offset:63728
	v_rcp_f32_e32 v6, v5
	s_nop 0
	v_mul_f32_e32 v148, v3, v6
	s_waitcnt lgkmcnt(2)
	v_pk_add_f32 v[6:7], v[166:167], v[170:171]
	s_waitcnt lgkmcnt(1)
	v_pk_add_f32 v[6:7], v[6:7], v[174:175]
	s_waitcnt lgkmcnt(0)
	v_pk_add_f32 v[6:7], v[6:7], v[178:179]
	v_rcp_f32_e32 v3, v4
	v_pk_mul_f32 v[6:7], v[6:7], s[0:1] op_sel_hi:[1,0]
	v_mul_f32_e32 v9, v2, v3
	s_nop 0
	v_fma_f32 v8, -v6, v6, v7
	v_max_f32_e32 v8, 0, v8
	v_add_f32_e32 v8, 0x358637bd, v8
	v_pk_add_f32 v[4:5], v[152:153], v[6:7] op_sel_hi:[1,0] neg_lo:[0,1] neg_hi:[0,1]
	v_add_u32_e32 v6, 5, v160
	v_rsq_f32_e32 v8, v8
	v_ashrrev_i32_e32 v7, 31, v6
	v_lshlrev_b64 v[6:7], 11, v[6:7]
	v_lshl_add_u64 v[6:7], v[78:79], 0, v[6:7]
	v_mov_b32_e32 v2, v8
	v_pk_mul_f32 v[2:3], v[4:5], v[2:3] op_sel_hi:[1,0]
	v_cvt_pk_bf16_f32 v8, v9, v148
	v_pk_fma_f32 v[2:3], v[144:145], v[2:3], v[146:147]
	global_store_dword v[6:7], v8, off
	v_mul_f32_e32 v4, 0xbfb8aa3b, v2
	v_mul_f32_e32 v5, 0xbfb8aa3b, v3
	v_exp_f32_e32 v4, v4
	v_exp_f32_e32 v5, v5
	s_nop 0
	v_pk_add_f32 v[4:5], v[4:5], 1.0 op_sel_hi:[1,0]
	s_nop 0
	s_nop 0
	v_rcp_f32_e32 v6, v5
	s_nop 0
	v_mul_f32_e32 v148, v3, v6
	v_pk_add_f32 v[6:7], v[168:169], v[172:173]
	v_pk_add_f32 v[6:7], v[6:7], v[176:177]
	v_pk_add_f32 v[6:7], v[6:7], v[180:181]
	v_rcp_f32_e32 v3, v4
	v_pk_mul_f32 v[6:7], v[6:7], s[0:1] op_sel_hi:[1,0]
	v_mul_f32_e32 v9, v2, v3
	s_nop 0
	v_fma_f32 v8, -v6, v6, v7
	v_max_f32_e32 v8, 0, v8
	v_add_f32_e32 v8, 0x358637bd, v8
	v_pk_add_f32 v[4:5], v[154:155], v[6:7] op_sel_hi:[1,0] neg_lo:[0,1] neg_hi:[0,1]
	v_add_u32_e32 v6, 6, v160
	v_rsq_f32_e32 v8, v8
	v_ashrrev_i32_e32 v7, 31, v6
	v_lshlrev_b64 v[6:7], 11, v[6:7]
	v_lshl_add_u64 v[6:7], v[78:79], 0, v[6:7]
	v_mov_b32_e32 v2, v8
	v_pk_mul_f32 v[2:3], v[4:5], v[2:3] op_sel_hi:[1,0]
	v_cvt_pk_bf16_f32 v8, v9, v148
	v_pk_fma_f32 v[2:3], v[144:145], v[2:3], v[146:147]
	global_store_dword v[6:7], v8, off
	v_mul_f32_e32 v4, 0xbfb8aa3b, v2
	v_mul_f32_e32 v5, 0xbfb8aa3b, v3
	v_exp_f32_e32 v4, v4
	v_exp_f32_e32 v5, v5
	s_nop 0
	v_pk_add_f32 v[4:5], v[4:5], 1.0 op_sel_hi:[1,0]
	s_nop 0
	s_nop 0
	v_rcp_f32_e32 v6, v5
	s_nop 0
	v_mul_f32_e32 v3, v3, v6
	v_rcp_f32_e32 v5, v4
	s_nop 0
	v_mul_f32_e32 v2, v2, v5
	v_cvt_pk_bf16_f32 v4, v2, v3
	v_add_u32_e32 v2, 7, v160
	v_ashrrev_i32_e32 v3, 31, v2
	v_lshlrev_b64 v[2:3], 11, v[2:3]
	v_lshl_add_u64 v[2:3], v[78:79], 0, v[2:3]
	global_store_dword v[2:3], v4, off
	s_barrier
	s_cbranch_scc0 .LBB0_189

; DI unsigned pk2(float a, float b) { fl2_t f = {a, b}; bf2_t r = __builtin_convertvector(f, bf2_t); return __builtin_bit_cast(unsigned, r); }
; #define HSUM(v) do { v += __shfl_xor(v, 16, 64); v += __shfl_xor(v, 8, 64); v += __shfl_xor(v, 4, 64); v += __shfl_xor(v, 2, 64); v += __shfl_xor(v, 1, 64); } while (0)
; DI void phase5(const Params& p, char* lds0) {
;     ...
;       float hv[32];
;       float ss = 0.f;
; #pragma unroll
;       for (int j = 0; j < 8; ++j) {
;         float4 v = nx[j];
;         hv[j * 4 + 0] = v.x; hv[j * 4 + 1] = v.y; hv[j * 4 + 2] = v.z; hv[j * 4 + 3] = v.w;
;         ss += v.x * v.x + v.y * v.y + v.z * v.z + v.w * v.w;
;       }
;       if (i + 1 < 8) {
;         const float* x1 = p.out + (size_t)(t + 2) * D;
; #pragma unroll
;         for (int j = 0; j < 8; ++j) nx[j] = *(const float4*)(x1 + j * 128 + l32 * 4);
;       }
;     ...
;       HSUM(ss);
;       const float rstd = rsqrtf(ss * (1.f / 1024.f) + 1e-6f);
; #pragma unroll
;       for (int j = 0; j < 8; ++j) {
;         const int c = j * 128 + l32 * 4;
;         hv[j * 4 + 0] = hv[j * 4 + 0] * rstd * csv[j].x + shv[j].x;
;         hv[j * 4 + 1] = hv[j * 4 + 1] * rstd * csv[j].y + shv[j].y;
;         hv[j * 4 + 2] = hv[j * 4 + 2] * rstd * csv[j].z + shv[j].z;
;         hv[j * 4 + 3] = hv[j * 4 + 3] * rstd * csv[j].w + shv[j].w;
;         u32x2 o; o[0] = pk2(hv[j * 4 + 0], hv[j * 4 + 1]); o[1] = pk2(hv[j * 4 + 2], hv[j * 4 + 3]);
;         *(u32x2*)(H + (size_t)t * D + c) = o;
;       }
.LBB0_259:
	s_waitcnt vmcnt(16)
	v_pk_mul_f32 v[160:161], v[94:95], v[94:95]
	s_waitcnt vmcnt(15)
	v_pk_mul_f32 v[164:165], v[90:91], v[90:91]
	v_pk_mul_f32 v[162:163], v[96:97], v[96:97]
	v_pk_mul_f32 v[166:167], v[92:93], v[92:93]
	v_add_f32_e32 v159, v161, v160
	v_add_f32_e32 v160, v165, v164
	v_add_f32_e32 v159, v162, v159
	v_add_f32_e32 v160, v166, v160
	s_waitcnt vmcnt(14)
	v_pk_mul_f32 v[168:169], v[86:87], v[86:87]
	v_add_f32_e32 v159, v163, v159
	v_add_f32_e32 v160, v167, v160
	v_pk_mul_f32 v[170:171], v[88:89], v[88:89]
	v_add_f32_e32 v159, v160, v159
	v_add_f32_e32 v160, v169, v168
	v_add_f32_e32 v160, v170, v160
	s_waitcnt vmcnt(13)
	v_pk_mul_f32 v[172:173], v[78:79], v[78:79]
	v_add_f32_e32 v160, v171, v160
	v_pk_mul_f32 v[188:189], v[80:81], v[80:81]
	v_add_f32_e32 v159, v160, v159
	v_add_f32_e32 v160, v173, v172
	v_add_f32_e32 v160, v188, v160
	s_waitcnt vmcnt(12)
	v_pk_mul_f32 v[190:191], v[70:71], v[70:71]
	v_add_f32_e32 v160, v189, v160
	v_pk_mul_f32 v[192:193], v[72:73], v[72:73]
	v_add_f32_e32 v159, v160, v159
	v_add_f32_e32 v160, v191, v190
	v_add_f32_e32 v160, v192, v160
	s_waitcnt vmcnt(11)
	v_pk_mul_f32 v[194:195], v[82:83], v[82:83]
	v_add_f32_e32 v160, v193, v160
	v_pk_mul_f32 v[196:197], v[84:85], v[84:85]
	v_add_f32_e32 v159, v160, v159
	v_add_f32_e32 v160, v194, v195
	v_add_f32_e32 v160, v160, v196
	s_waitcnt vmcnt(10)
	v_pk_mul_f32 v[198:199], v[74:75], v[74:75]
	v_add_f32_e32 v160, v160, v197
	v_pk_mul_f32 v[200:201], v[76:77], v[76:77]
	v_add_f32_e32 v159, v160, v159
	v_add_f32_e32 v160, v198, v199
	v_add_f32_e32 v160, v160, v200
	s_waitcnt vmcnt(9)
	v_pk_mul_f32 v[202:203], v[66:67], v[66:67]
	v_add_f32_e32 v160, v160, v201
	v_pk_mul_f32 v[204:205], v[68:69], v[68:69]
	v_add_f32_e32 v159, v159, v160
	v_add_f32_e32 v160, v202, v203
	v_add_f32_e32 v160, v160, v204
	v_add_f32_e32 v160, v160, v205
	v_add_f32_e32 v159, v159, v160
	ds_bpermute_b32 v160, v176, v159
	s_waitcnt lgkmcnt(0)
	v_add_f32_e32 v159, v159, v160
	ds_bpermute_b32 v160, v177, v159
	s_waitcnt lgkmcnt(0)
	v_add_f32_e32 v159, v159, v160
	ds_bpermute_b32 v160, v178, v159
	s_waitcnt lgkmcnt(0)
	v_add_f32_e32 v159, v159, v160
	ds_bpermute_b32 v160, v179, v159
	s_waitcnt lgkmcnt(0)
	v_add_f32_e32 v159, v159, v160
	ds_bpermute_b32 v160, v180, v159
	s_waitcnt lgkmcnt(0)
	v_add_f32_e32 v159, v159, v160
	v_fmamk_f32 v159, v159, 0x3a800000, v182
	v_mul_f32_e32 v160, 0x4b800000, v159
	v_cmp_gt_f32_e32 vcc, s40, v159
	s_nop 1
	v_cndmask_b32_e32 v159, v159, v160, vcc
	v_rsq_f32_e32 v159, v159
	s_nop 0
	v_mul_f32_e32 v160, 0x45800000, v159
	v_cndmask_b32_e32 v168, v159, v160, vcc
	v_pk_mul_f32 v[94:95], v[94:95], v[168:169] op_sel_hi:[1,0]
	v_ashrrev_i32_e32 v159, 31, v158
	v_pk_fma_f32 v[160:161], v[126:127], v[94:95], v[2:3]
	v_pk_mul_f32 v[94:95], v[96:97], v[168:169] op_sel_hi:[1,0]
	v_lshlrev_b64 v[164:165], 11, v[158:159]
	v_pk_fma_f32 v[162:163], v[128:129], v[94:95], v[4:5]
	v_pk_mul_f32 v[90:91], v[90:91], v[168:169] op_sel_hi:[1,0]
	v_cvt_pk_bf16_f32 v94, v160, v161
	v_cvt_pk_bf16_f32 v95, v162, v163
	v_lshl_add_u64 v[166:167], v[110:111], 0, v[164:165]
	v_pk_fma_f32 v[164:165], v[130:131], v[90:91], v[6:7]
	v_pk_mul_f32 v[90:91], v[92:93], v[168:169] op_sel_hi:[1,0]
	global_store_dwordx2 v[166:167], v[94:95], off
	v_pk_fma_f32 v[94:95], v[132:133], v[90:91], v[8:9]
	v_cvt_pk_bf16_f32 v90, v164, v165
	v_cvt_pk_bf16_f32 v91, v94, v95
	v_pk_mul_f32 v[86:87], v[86:87], v[168:169] op_sel_hi:[1,0]
	global_store_dwordx2 v[166:167], v[90:91], off offset:256
	v_pk_fma_f32 v[90:91], v[134:135], v[86:87], v[10:11]
	v_pk_mul_f32 v[86:87], v[88:89], v[168:169] op_sel_hi:[1,0]
	v_pk_mul_f32 v[78:79], v[78:79], v[168:169] op_sel_hi:[1,0]
	v_pk_fma_f32 v[92:93], v[136:137], v[86:87], v[12:13]
	v_pk_mul_f32 v[70:71], v[70:71], v[168:169] op_sel_hi:[1,0]
	v_cvt_pk_bf16_f32 v86, v90, v91
	v_cvt_pk_bf16_f32 v87, v92, v93
	v_pk_fma_f32 v[96:97], v[138:139], v[78:79], v[14:15]
	v_pk_mul_f32 v[78:79], v[80:81], v[168:169] op_sel_hi:[1,0]
	v_pk_fma_f32 v[80:81], v[142:143], v[70:71], v[18:19]
	v_pk_mul_f32 v[70:71], v[72:73], v[168:169] op_sel_hi:[1,0]
	global_store_dwordx2 v[166:167], v[86:87], off offset:512
	v_pk_fma_f32 v[86:87], v[144:145], v[70:71], v[20:21]
	v_cvt_pk_bf16_f32 v70, v80, v81
	v_cvt_pk_bf16_f32 v71, v86, v87
	v_pk_fma_f32 v[88:89], v[140:141], v[78:79], v[16:17]
	global_store_dwordx2 v[166:167], v[70:71], off offset:1024
	v_pk_mul_f32 v[70:71], v[82:83], v[168:169] op_sel_hi:[1,0]
	v_cvt_pk_bf16_f32 v78, v96, v97
	v_cvt_pk_bf16_f32 v79, v88, v89
	v_pk_fma_f32 v[82:83], v[146:147], v[70:71], v[22:23]
	v_pk_mul_f32 v[70:71], v[84:85], v[168:169] op_sel_hi:[1,0]
	global_store_dwordx2 v[166:167], v[78:79], off offset:768
	v_pk_fma_f32 v[78:79], v[148:149], v[70:71], v[24:25]
	v_cvt_pk_bf16_f32 v70, v82, v83
	v_cvt_pk_bf16_f32 v71, v78, v79
	global_store_dwordx2 v[166:167], v[70:71], off offset:1280
	v_pk_mul_f32 v[70:71], v[74:75], v[168:169] op_sel_hi:[1,0]
	v_pk_mul_f32 v[72:73], v[76:77], v[168:169] op_sel_hi:[1,0]
	v_pk_fma_f32 v[70:71], v[150:151], v[70:71], v[26:27]
	v_pk_fma_f32 v[72:73], v[152:153], v[72:73], v[28:29]
	v_cvt_pk_bf16_f32 v74, v70, v71
	v_cvt_pk_bf16_f32 v75, v72, v73
	global_store_dwordx2 v[166:167], v[74:75], off offset:1536
	ds_read_b128 v[74:77], v102 offset:9216
	ds_read_b128 v[188:191], v102 offset:9728
	v_mov_b32_e32 v204, v91
	v_mov_b32_e32 v205, v97
	v_pk_mul_f32 v[170:171], v[66:67], v[168:169] op_sel_hi:[1,0]
	v_pk_mul_f32 v[66:67], v[68:69], v[168:169] op_sel_hi:[1,0]
	s_waitcnt lgkmcnt(0)
; #define HSUM(v) do { v += __shfl_xor(v, 16, 64); v += __shfl_xor(v, 8, 64); v += __shfl_xor(v, 4, 64); v += __shfl_xor(v, 2, 64); v += __shfl_xor(v, 1, 64); } while (0)
; DI void phase5(const Params& p, char* lds0) {
;     ...
;       float lg[4];
; #pragma unroll
;       for (int n = 0; n < 4; ++n) {
;         float a = 0.f;
; #pragma unroll
;         for (int j = 0; j < 8; ++j) {
;           float4 wv = *(const float4*)(wg + n * 1024 + j * 128 + l32 * 4);
;           a += hv[j * 4 + 0] * wv.x + hv[j * 4 + 1] * wv.y + hv[j * 4 + 2] * wv.z + hv[j * 4 + 3] * wv.w;
;         }
;         HSUM(a);
;         lg[n] = a + p.b_rg[n];
;       }
	v_mov_b32_e32 v85, v188
	v_mov_b32_e32 v188, v75
	v_mov_b32_e32 v84, v74
	v_mov_b32_e32 v68, v90
	v_mov_b32_e32 v69, v96
	v_pk_mul_f32 v[74:75], v[204:205], v[188:189]
	v_mov_b32_e32 v206, v92
	v_pk_fma_f32 v[74:75], v[68:69], v[84:85], v[74:75]
	v_mov_b32_e32 v84, v76
	v_mov_b32_e32 v85, v190
	v_mov_b32_e32 v207, v88
	v_pk_fma_f32 v[84:85], v[206:207], v[84:85], v[74:75]
	v_mov_b32_e32 v190, v77
	ds_read_b128 v[74:77], v102 offset:10240
	ds_read_b128 v[192:195], v102 offset:10752
	v_mov_b32_e32 v208, v93
	v_mov_b32_e32 v209, v89
	v_pk_fma_f32 v[168:169], v[208:209], v[190:191], v[84:85]
	v_mov_b32_e32 v212, v81
	s_waitcnt lgkmcnt(0)
	v_mov_b32_e32 v85, v192
	v_mov_b32_e32 v192, v75
	v_mov_b32_e32 v213, v83
	v_mov_b32_e32 v84, v74
	v_mov_b32_e32 v210, v80
	v_mov_b32_e32 v211, v82
	v_pk_mul_f32 v[74:75], v[212:213], v[192:193]
	v_mov_b32_e32 v188, v76
	v_pk_fma_f32 v[84:85], v[210:211], v[84:85], v[74:75]
	v_mov_b32_e32 v189, v194
	v_mov_b32_e32 v74, v86
	v_mov_b32_e32 v75, v78
	v_pk_fma_f32 v[84:85], v[74:75], v[188:189], v[84:85]
	ds_read_b128 v[188:191], v102 offset:8192
	ds_read_b128 v[196:199], v102 offset:12288
	v_mov_b32_e32 v194, v77
	v_mov_b32_e32 v76, v87
	v_mov_b32_e32 v77, v79
	v_pk_fma_f32 v[84:85], v[76:77], v[194:195], v[84:85]
	ds_read_b128 v[192:195], v102 offset:8704
	ds_read_b128 v[200:203], v102 offset:12800
	s_waitcnt lgkmcnt(2)
	v_pk_mov_b32 v[214:215], v[188:189], v[196:197] op_sel:[1,0]
	v_mov_b32_e32 v189, v197
	v_pk_mul_f32 v[188:189], v[188:189], v[160:161]
	v_mov_b32_e32 v196, v190
	v_pk_fma_f32 v[188:189], v[214:215], v[160:161], v[188:189] op_sel:[0,1,0] op_sel_hi:[1,0,1]
	v_mov_b32_e32 v197, v198
	v_pk_fma_f32 v[188:189], v[162:163], v[196:197], v[188:189] op_sel_hi:[0,1,1]
	v_mov_b32_e32 v198, v191
	v_pk_fma_f32 v[188:189], v[162:163], v[198:199], v[188:189] op_sel:[1,0,0]
	s_waitcnt vmcnt(7)
	v_pk_fma_f32 v[66:67], v[156:157], v[66:67], v[32:33]
	v_pk_add_f32 v[214:215], v[188:189], 0 op_sel_hi:[1,0]
	s_waitcnt lgkmcnt(0)
	v_pk_mov_b32 v[188:189], v[192:193], v[200:201] op_sel:[1,0]
	v_mov_b32_e32 v193, v201
	v_pk_mul_f32 v[190:191], v[164:165], v[192:193]
	v_cvt_pk_bf16_f32 v173, v66, v67
	v_pk_fma_f32 v[188:189], v[164:165], v[188:189], v[190:191] op_sel:[1,0,0] op_sel_hi:[0,1,1]
	v_mov_b32_e32 v190, v194
	v_mov_b32_e32 v191, v202
	v_pk_fma_f32 v[192:193], v[94:95], v[190:191], v[188:189] op_sel_hi:[0,1,1]
	ds_read_b128 v[188:191], v102 offset:13312
	ds_read_b128 v[196:199], v102 offset:13824
	v_mov_b32_e32 v202, v195
	v_pk_fma_f32 v[192:193], v[94:95], v[202:203], v[192:193] op_sel:[1,0,0]
	s_nop 0
	v_pk_add_f32 v[214:215], v[214:215], v[192:193]
	s_waitcnt lgkmcnt(0)
	v_mov_b32_e32 v193, v196
	v_mov_b32_e32 v196, v189
	v_mov_b32_e32 v192, v188
	v_pk_mul_f32 v[188:189], v[204:205], v[196:197]
	v_mov_b32_e32 v196, v190
	v_pk_fma_f32 v[188:189], v[68:69], v[192:193], v[188:189]
	ds_read_b128 v[192:195], v102 offset:14336
	ds_read_b128 v[200:203], v102 offset:14848
	v_mov_b32_e32 v197, v198
	v_pk_fma_f32 v[188:189], v[206:207], v[196:197], v[188:189]
	v_mov_b32_e32 v198, v191
	v_pk_fma_f32 v[216:217], v[208:209], v[198:199], v[188:189]
	s_waitcnt lgkmcnt(0)
	v_mov_b32_e32 v189, v200
	v_mov_b32_e32 v200, v193
	v_mov_b32_e32 v188, v192
	v_pk_mul_f32 v[190:191], v[212:213], v[200:201]
	v_mov_b32_e32 v196, v194
	v_pk_fma_f32 v[192:193], v[210:211], v[188:189], v[190:191]
	ds_read_b128 v[188:191], v102 offset:16384
	v_mov_b32_e32 v197, v202
	v_pk_fma_f32 v[192:193], v[74:75], v[196:197], v[192:193]
	v_mov_b32_e32 v202, v195
	v_pk_fma_f32 v[218:219], v[76:77], v[202:203], v[192:193]
	ds_read_b128 v[192:195], v102 offset:16896
	s_waitcnt lgkmcnt(1)
	v_mul_f32_e32 v172, v161, v189
	v_fmac_f32_e32 v172, v160, v188
	v_fmac_f32_e32 v172, v162, v190
	v_fmac_f32_e32 v172, v163, v191
	ds_read_b128 v[188:191], v102 offset:17408
	ds_read_b128 v[196:199], v102 offset:17920
	s_waitcnt lgkmcnt(2)
	v_mul_f32_e32 v193, v165, v193
	v_fmac_f32_e32 v193, v164, v192
	v_fmac_f32_e32 v193, v94, v194
	v_add_f32_e32 v172, 0, v172
	v_fmac_f32_e32 v193, v95, v195
	v_add_f32_e32 v172, v172, v193
	s_waitcnt lgkmcnt(0)
	v_mov_b32_e32 v193, v196
	v_mov_b32_e32 v196, v189
	v_mov_b32_e32 v192, v188
	v_pk_mul_f32 v[188:189], v[204:205], v[196:197]
	s_nop 0
	v_pk_fma_f32 v[188:189], v[68:69], v[192:193], v[188:189]
	v_mov_b32_e32 v192, v190
	v_mov_b32_e32 v193, v198
	v_pk_fma_f32 v[196:197], v[206:207], v[192:193], v[188:189]
	v_mov_b32_e32 v198, v191
	ds_read_b128 v[188:191], v102 offset:18432
	ds_read_b128 v[192:195], v102 offset:18944
	v_pk_fma_f32 v[196:197], v[208:209], v[198:199], v[196:197]
	s_nop 0
	v_add_f32_e32 v172, v172, v196
	v_add_f32_e32 v172, v172, v197
	s_waitcnt lgkmcnt(0)
	v_mov_b32_e32 v197, v192
	v_mov_b32_e32 v192, v189
	v_mov_b32_e32 v196, v188
	v_pk_mul_f32 v[188:189], v[212:213], v[192:193]
	v_mov_b32_e32 v192, v190
	v_pk_fma_f32 v[188:189], v[210:211], v[196:197], v[188:189]
	v_mov_b32_e32 v193, v194
	v_pk_fma_f32 v[192:193], v[74:75], v[192:193], v[188:189]
	v_mov_b32_e32 v194, v191
	ds_read_b128 v[188:191], v102 offset:20480
	v_pk_fma_f32 v[192:193], v[76:77], v[194:195], v[192:193]
	s_nop 0
	v_add_f32_e32 v172, v172, v192
	v_add_f32_e32 v220, v172, v193
	ds_read_b128 v[192:195], v102 offset:20992
	s_waitcnt lgkmcnt(1)
	v_mul_f32_e32 v172, v161, v189
	v_fmac_f32_e32 v172, v160, v188
	v_fmac_f32_e32 v172, v162, v190
	v_fmac_f32_e32 v172, v163, v191
	ds_read_b128 v[188:191], v102 offset:21504
	ds_read_b128 v[196:199], v102 offset:22016
	s_waitcnt lgkmcnt(2)
	v_mul_f32_e32 v193, v165, v193
	v_fmac_f32_e32 v193, v164, v192
	v_fmac_f32_e32 v193, v94, v194
	v_add_f32_e32 v172, 0, v172
	v_fmac_f32_e32 v193, v95, v195
	v_add_f32_e32 v172, v172, v193
	s_waitcnt lgkmcnt(0)
; #define HSUM(v) do { v += __shfl_xor(v, 16, 64); v += __shfl_xor(v, 8, 64); v += __shfl_xor(v, 4, 64); v += __shfl_xor(v, 2, 64); v += __shfl_xor(v, 1, 64); } while (0)
; DI void phase5(const Params& p, char* lds0) {
;     ...
;       float lg[4];
; #pragma unroll
;       for (int n = 0; n < 4; ++n) {
;         float a = 0.f;
; #pragma unroll
;         for (int j = 0; j < 8; ++j) {
;           float4 wv = *(const float4*)(wg + n * 1024 + j * 128 + l32 * 4);
;           a += hv[j * 4 + 0] * wv.x + hv[j * 4 + 1] * wv.y + hv[j * 4 + 2] * wv.z + hv[j * 4 + 3] * wv.w;
;         }
;         HSUM(a);
;         lg[n] = a + p.b_rg[n];
;       }
	v_mov_b32_e32 v193, v196
	v_mov_b32_e32 v196, v189
	v_mov_b32_e32 v192, v188
	v_pk_mul_f32 v[188:189], v[204:205], v[196:197]
	s_nop 0
	v_pk_fma_f32 v[68:69], v[68:69], v[192:193], v[188:189]
	v_mov_b32_e32 v188, v190
	v_mov_b32_e32 v189, v198
	v_pk_fma_f32 v[68:69], v[206:207], v[188:189], v[68:69]
	v_mov_b32_e32 v198, v191
	ds_read_b128 v[188:191], v102 offset:22528
	ds_read_b128 v[192:195], v102 offset:23040
	v_pk_fma_f32 v[68:69], v[208:209], v[198:199], v[68:69]
	ds_read_b128 v[196:199], v102 offset:11264
	ds_read_b128 v[200:203], v102 offset:11776
	v_add_f32_e32 v68, v172, v68
	v_add_f32_e32 v221, v68, v69
	s_waitcnt lgkmcnt(2)
	v_mov_b32_e32 v69, v192
	v_mov_b32_e32 v192, v189
	v_mov_b32_e32 v68, v188
	v_pk_mul_f32 v[188:189], v[212:213], v[192:193]
	s_waitcnt lgkmcnt(1)
	v_mov_b32_e32 v204, v198
	v_pk_fma_f32 v[188:189], v[210:211], v[68:69], v[188:189]
	v_pk_fma_f32 v[68:69], v[154:155], v[170:171], v[30:31]
	s_waitcnt lgkmcnt(0)
	v_mov_b32_e32 v205, v202
	v_cvt_pk_bf16_f32 v172, v68, v69
	global_store_dwordx2 v[166:167], v[172:173], off offset:1792
	v_mov_b32_e32 v166, v196
	v_mov_b32_e32 v167, v200
	v_mov_b32_e32 v200, v197
	v_mov_b32_e32 v202, v199
	ds_read_b128 v[170:173], v102 offset:15360
	ds_read_b128 v[196:199], v102 offset:15872
	v_mov_b32_e32 v212, v71
	v_mov_b32_e32 v213, v69
	v_mov_b32_e32 v210, v70
	v_mov_b32_e32 v211, v68
	v_pk_mul_f32 v[200:201], v[212:213], v[200:201]
	v_mov_b32_e32 v206, v72
	v_mov_b32_e32 v207, v66
	v_pk_fma_f32 v[166:167], v[210:211], v[166:167], v[200:201]
	v_mov_b32_e32 v208, v73
	v_mov_b32_e32 v209, v67
	v_pk_fma_f32 v[166:167], v[206:207], v[204:205], v[166:167]
	v_mov_b32_e32 v192, v190
	v_pk_fma_f32 v[200:201], v[208:209], v[202:203], v[166:167]
	s_waitcnt lgkmcnt(0)
	v_mov_b32_e32 v167, v196
	v_mov_b32_e32 v196, v171
	v_mov_b32_e32 v166, v170
	v_mov_b32_e32 v170, v172
	v_mov_b32_e32 v171, v198
	v_mov_b32_e32 v198, v173
	v_pk_mul_f32 v[172:173], v[212:213], v[196:197]
	v_mov_b32_e32 v196, v84
	v_pk_fma_f32 v[166:167], v[210:211], v[166:167], v[172:173]
	v_mov_b32_e32 v197, v218
	v_pk_fma_f32 v[166:167], v[206:207], v[170:171], v[166:167]
	v_mov_b32_e32 v218, v85
	v_pk_fma_f32 v[170:171], v[208:209], v[198:199], v[166:167]
	v_mov_b32_e32 v166, v168
	v_mov_b32_e32 v167, v216
	v_pk_add_f32 v[166:167], v[214:215], v[166:167]
	v_mov_b32_e32 v216, v169
	v_pk_add_f32 v[172:173], v[166:167], v[216:217]
	global_load_dwordx4 v[166:169], v101, s[28:29]
	v_pk_add_f32 v[172:173], v[172:173], v[196:197]
	v_mov_b32_e32 v193, v194
	v_pk_add_f32 v[84:85], v[172:173], v[218:219]
	v_mov_b32_e32 v172, v200
	v_mov_b32_e32 v173, v170
	v_pk_add_f32 v[84:85], v[84:85], v[172:173]
	v_mov_b32_e32 v170, v201
	v_pk_add_f32 v[84:85], v[84:85], v[170:171]
	ds_bpermute_b32 v170, v176, v84
	ds_bpermute_b32 v171, v176, v85
	v_pk_fma_f32 v[74:75], v[74:75], v[192:193], v[188:189]
	v_mov_b32_e32 v194, v191
	v_pk_fma_f32 v[74:75], v[76:77], v[194:195], v[74:75]
	s_waitcnt lgkmcnt(0)
	v_pk_add_f32 v[84:85], v[84:85], v[170:171]
	v_add_f32_e32 v74, v221, v74
	v_add_f32_e32 v192, v74, v75
	ds_read_b128 v[74:77], v102 offset:19456
	ds_read_b128 v[170:173], v102 offset:19968
	ds_bpermute_b32 v188, v177, v84
	ds_bpermute_b32 v189, v177, v85
	s_waitcnt lgkmcnt(3)
	v_mov_b32_e32 v190, v74
	s_waitcnt lgkmcnt(2)
	v_mov_b32_e32 v191, v170
	v_mov_b32_e32 v170, v75
	v_mov_b32_e32 v74, v76
	v_mov_b32_e32 v75, v172
	v_mov_b32_e32 v172, v77
	v_pk_mul_f32 v[76:77], v[212:213], v[170:171]
	s_waitcnt lgkmcnt(0)
	v_pk_add_f32 v[84:85], v[84:85], v[188:189]
	v_pk_fma_f32 v[76:77], v[210:211], v[190:191], v[76:77]
	ds_bpermute_b32 v188, v178, v84
	v_pk_fma_f32 v[74:75], v[206:207], v[74:75], v[76:77]
	ds_bpermute_b32 v189, v178, v85
	v_pk_fma_f32 v[190:191], v[208:209], v[172:173], v[74:75]
	ds_read_b128 v[74:77], v102 offset:23552
	ds_read_b128 v[170:173], v102 offset:24064
	v_add_f32_e32 v190, v220, v190
	v_add_f32_e32 v193, v190, v191
	ds_bpermute_b32 v194, v176, v193
	s_waitcnt lgkmcnt(2)
	v_mov_b32_e32 v190, v74
	s_waitcnt lgkmcnt(1)
	v_mov_b32_e32 v191, v170
	v_mov_b32_e32 v170, v75
	v_mov_b32_e32 v74, v76
	v_mov_b32_e32 v75, v172
	v_mov_b32_e32 v172, v77
	v_pk_mul_f32 v[76:77], v[212:213], v[170:171]
	s_nop 0
	v_pk_fma_f32 v[76:77], v[210:211], v[190:191], v[76:77]
	s_nop 0
	v_pk_fma_f32 v[74:75], v[206:207], v[74:75], v[76:77]
	s_nop 0
	v_pk_fma_f32 v[74:75], v[208:209], v[172:173], v[74:75]
	s_nop 0
	v_add_f32_e32 v74, v192, v74
	v_add_f32_e32 v76, v74, v75
	ds_bpermute_b32 v77, v176, v76
	v_pk_add_f32 v[74:75], v[84:85], v[188:189]
	s_waitcnt lgkmcnt(1)
	v_add_f32_e32 v84, v193, v194
	ds_bpermute_b32 v85, v177, v84
	s_waitcnt lgkmcnt(1)
	v_add_f32_e32 v170, v76, v77
	ds_bpermute_b32 v171, v177, v170
	ds_bpermute_b32 v76, v179, v74
	s_waitcnt lgkmcnt(2)
	v_add_f32_e32 v84, v84, v85
	ds_bpermute_b32 v85, v178, v84
	ds_bpermute_b32 v77, v179, v75
	s_waitcnt lgkmcnt(3)
	v_add_f32_e32 v170, v170, v171
	ds_bpermute_b32 v171, v178, v170
	s_waitcnt lgkmcnt(2)
	v_add_f32_e32 v84, v84, v85
	ds_bpermute_b32 v85, v179, v84
	s_waitcnt lgkmcnt(2)
	v_pk_add_f32 v[74:75], v[74:75], v[76:77]
	s_waitcnt lgkmcnt(1)
	v_add_f32_e32 v170, v170, v171
	ds_bpermute_b32 v171, v179, v170
	ds_bpermute_b32 v76, v180, v74
	ds_bpermute_b32 v77, v180, v75
	s_waitcnt lgkmcnt(3)
	v_add_f32_e32 v84, v84, v85
	ds_bpermute_b32 v85, v180, v84
	s_waitcnt lgkmcnt(3)
	v_add_f32_e32 v170, v170, v171
	ds_bpermute_b32 v171, v180, v170
	s_waitcnt lgkmcnt(2)
	v_pk_add_f32 v[74:75], v[74:75], v[76:77]
	s_waitcnt lgkmcnt(1)
	v_add_f32_e32 v76, v84, v85
	s_waitcnt vmcnt(0)
	v_pk_add_f32 v[74:75], v[166:167], v[74:75]
	v_add_f32_e32 v168, v168, v76
	s_waitcnt lgkmcnt(0)
; DI void phase5(const Params& p, char* lds0) {
;     ...
;       int g = 0; float gm = lg[0];
; #pragma unroll
;       for (int n = 1; n < 4; ++n) if (lg[n] > gm) { gm = lg[n]; g = n; }
;       float den = 0.f;
; #pragma unroll
;       for (int n = 0; n < 4; ++n) den += __expf(lg[n] - gm);
;       const float pgrp = 1.f / den;
;       float le[8];
; #pragma unroll
;       for (int e = 0; e < 8; ++e) {
;         const float* wr = wg + (4 + g * 8 + e) * 1024;
;         float a = 0.f;
; #pragma unroll
;         for (int j = 0; j < 8; ++j) {
;           float4 wv = *(const float4*)(wr + j * 128 + l32 * 4);
;           a += hv[j * 4 + 0] * wv.x + hv[j * 4 + 1] * wv.y + hv[j * 4 + 2] * wv.z + hv[j * 4 + 3] * wv.w;
	v_add_f32_e32 v76, v170, v171
	v_cmp_gt_f32_e32 vcc, v75, v74
	v_add_f32_e32 v167, v169, v76
	s_nop 0
	v_cndmask_b32_e32 v76, v74, v75, vcc
	v_cmp_gt_f32_e64 s[6:7], v168, v76
	s_nop 1
	v_cndmask_b32_e64 v169, v76, v168, s[6:7]
	v_cndmask_b32_e64 v76, 0, 8, vcc
	v_cndmask_b32_e64 v76, v76, 16, s[6:7]
	v_cmp_gt_f32_e32 vcc, v167, v169
	s_nop 1
	v_cndmask_b32_e64 v166, v76, 24, vcc
	v_lshl_or_b32 v170, v166, 12, v102
	ds_read_b128 v[188:191], v170 offset:26624
	ds_read_b128 v[192:195], v170 offset:27136
	ds_read_b128 v[196:199], v170 offset:24576
	ds_read_b128 v[200:203], v170 offset:28672
	ds_read_b128 v[204:207], v170 offset:27648
	ds_read_b128 v[208:211], v170 offset:28160
	ds_read_b128 v[212:215], v170 offset:25088
	ds_read_b128 v[216:219], v170 offset:29184
	s_waitcnt lgkmcnt(4)
	v_pk_mov_b32 v[76:77], v[196:197], v[200:201] op_sel:[1,0]
	v_mov_b32_e32 v197, v201
	v_pk_mul_f32 v[84:85], v[160:161], v[196:197]
	s_nop 0
	v_pk_fma_f32 v[76:77], v[160:161], v[76:77], v[84:85] op_sel:[1,0,0] op_sel_hi:[0,1,1]
	v_mov_b32_e32 v84, v198
	v_mov_b32_e32 v85, v202
	v_pk_fma_f32 v[76:77], v[162:163], v[84:85], v[76:77] op_sel_hi:[0,1,1]
	v_mov_b32_e32 v202, v199
	v_pk_fma_f32 v[76:77], v[162:163], v[202:203], v[76:77] op_sel:[1,0,0]
	s_waitcnt lgkmcnt(0)
	v_pk_mov_b32 v[84:85], v[212:213], v[216:217] op_sel:[1,0]
	v_mov_b32_e32 v213, v217
	ds_read_b128 v[196:199], v170 offset:26112
	ds_read_b128 v[200:203], v170 offset:25600
	ds_read_b128 v[220:223], v170 offset:29696
	v_pk_mul_f32 v[172:173], v[164:165], v[212:213]
	v_pk_add_f32 v[76:77], v[76:77], 0 op_sel_hi:[1,0]
	v_pk_fma_f32 v[84:85], v[164:165], v[84:85], v[172:173] op_sel:[1,0,0] op_sel_hi:[0,1,1]
	v_mov_b32_e32 v172, v214
	v_mov_b32_e32 v173, v218
	v_pk_fma_f32 v[84:85], v[94:95], v[172:173], v[84:85] op_sel_hi:[0,1,1]
	v_mov_b32_e32 v218, v215
	v_pk_fma_f32 v[84:85], v[94:95], v[218:219], v[84:85] op_sel:[1,0,0]
	ds_read_b128 v[212:215], v170 offset:30208
	v_pk_add_f32 v[76:77], v[76:77], v[84:85]
	s_waitcnt lgkmcnt(1)
	v_pk_mov_b32 v[84:85], v[200:201], v[220:221] op_sel:[1,0]
	v_mov_b32_e32 v201, v221
	v_pk_mul_f32 v[172:173], v[90:91], v[200:201]
	s_nop 0
	v_pk_fma_f32 v[84:85], v[90:91], v[84:85], v[172:173] op_sel:[1,0,0] op_sel_hi:[0,1,1]
	v_mov_b32_e32 v172, v202
	v_mov_b32_e32 v173, v222
	v_pk_fma_f32 v[84:85], v[92:93], v[172:173], v[84:85] op_sel_hi:[0,1,1]
	v_mov_b32_e32 v222, v203
	v_pk_fma_f32 v[84:85], v[92:93], v[222:223], v[84:85] op_sel:[1,0,0]
	ds_read_b128 v[200:203], v170 offset:30720
	v_pk_add_f32 v[76:77], v[76:77], v[84:85]
	s_waitcnt lgkmcnt(1)
	v_pk_mov_b32 v[84:85], v[196:197], v[212:213] op_sel:[1,0]
	v_mov_b32_e32 v197, v213
	v_pk_mul_f32 v[172:173], v[96:97], v[196:197]
	s_nop 0
	v_pk_fma_f32 v[84:85], v[96:97], v[84:85], v[172:173] op_sel:[1,0,0] op_sel_hi:[0,1,1]
	v_mov_b32_e32 v172, v198
	v_mov_b32_e32 v173, v214
	v_pk_fma_f32 v[84:85], v[88:89], v[172:173], v[84:85] op_sel_hi:[0,1,1]
	v_mov_b32_e32 v214, v199
	v_pk_fma_f32 v[84:85], v[88:89], v[214:215], v[84:85] op_sel:[1,0,0]
	ds_read_b128 v[196:199], v170 offset:31232
	v_pk_add_f32 v[76:77], v[76:77], v[84:85]
	s_waitcnt lgkmcnt(1)
	v_pk_mov_b32 v[84:85], v[188:189], v[200:201] op_sel:[1,0]
	v_mov_b32_e32 v189, v201
	v_pk_mul_f32 v[172:173], v[80:81], v[188:189]
	s_nop 0
	v_pk_fma_f32 v[84:85], v[80:81], v[84:85], v[172:173] op_sel:[1,0,0] op_sel_hi:[0,1,1]
	v_mov_b32_e32 v172, v190
	v_mov_b32_e32 v173, v202
	v_pk_fma_f32 v[84:85], v[86:87], v[172:173], v[84:85] op_sel_hi:[0,1,1]
	v_mov_b32_e32 v202, v191
	v_pk_fma_f32 v[84:85], v[86:87], v[202:203], v[84:85] op_sel:[1,0,0]
	ds_read_b128 v[188:191], v170 offset:31744
	v_pk_add_f32 v[76:77], v[76:77], v[84:85]
	v_mov_b32_e32 v84, v193
	s_waitcnt lgkmcnt(1)
	v_mov_b32_e32 v85, v196
	v_pk_mul_f32 v[84:85], v[82:83], v[84:85] op_sel:[1,0] op_sel_hi:[0,1]
	v_mov_b32_e32 v193, v197
	v_pk_fma_f32 v[84:85], v[82:83], v[192:193], v[84:85]
	v_mov_b32_e32 v172, v194
	v_mov_b32_e32 v173, v198
	v_pk_fma_f32 v[84:85], v[78:79], v[172:173], v[84:85] op_sel_hi:[0,1,1]
	v_mov_b32_e32 v198, v195
	v_pk_fma_f32 v[84:85], v[78:79], v[198:199], v[84:85] op_sel:[1,0,0]
	ds_read_b128 v[192:195], v170 offset:32256
	v_pk_add_f32 v[76:77], v[76:77], v[84:85]
	s_waitcnt lgkmcnt(1)
	v_mov_b32_e32 v84, v188
	v_mov_b32_e32 v85, v205
	v_pk_mul_f32 v[84:85], v[70:71], v[84:85]
	v_mov_b32_e32 v205, v189
	v_pk_fma_f32 v[84:85], v[70:71], v[204:205], v[84:85] op_sel:[0,0,1] op_sel_hi:[1,1,0]
	v_mov_b32_e32 v172, v206
	v_mov_b32_e32 v173, v190
	v_pk_fma_f32 v[84:85], v[72:73], v[172:173], v[84:85] op_sel_hi:[0,1,1]
	v_mov_b32_e32 v190, v207
	v_pk_fma_f32 v[84:85], v[72:73], v[190:191], v[84:85] op_sel:[1,0,0]
	ds_read_b128 v[188:191], v170 offset:32768
	v_pk_add_f32 v[76:77], v[76:77], v[84:85]
	s_waitcnt lgkmcnt(1)
	v_pk_mov_b32 v[84:85], v[208:209], v[192:193] op_sel:[1,0]
	v_mov_b32_e32 v209, v193
	v_pk_mul_f32 v[84:85], v[68:69], v[84:85] op_sel:[1,0] op_sel_hi:[0,1]
	v_pk_fma_f32 v[84:85], v[68:69], v[208:209], v[84:85]
	v_mov_b32_e32 v172, v210
	v_mov_b32_e32 v173, v194
	v_pk_fma_f32 v[84:85], v[66:67], v[172:173], v[84:85] op_sel_hi:[0,1,1]
	v_mov_b32_e32 v194, v211
	v_pk_fma_f32 v[84:85], v[66:67], v[194:195], v[84:85] op_sel:[1,0,0]
	ds_read_b128 v[192:195], v170 offset:33280
	s_waitcnt lgkmcnt(1)
	v_mul_f32_e32 v171, v161, v189
	v_fmac_f32_e32 v171, v160, v188
	v_fmac_f32_e32 v171, v162, v190
	v_fmac_f32_e32 v171, v163, v191
	ds_read_b128 v[188:191], v170 offset:33792
	s_waitcnt lgkmcnt(1)
	v_mul_f32_e32 v172, v165, v193
	v_fmac_f32_e32 v172, v164, v192
	v_fmac_f32_e32 v172, v94, v194
	v_add_f32_e32 v171, 0, v171
	v_fmac_f32_e32 v172, v95, v195
	ds_read_b128 v[192:195], v170 offset:34304
	v_add_f32_e32 v171, v171, v172
	s_waitcnt lgkmcnt(1)
; #define HSUM(v) do { v += __shfl_xor(v, 16, 64); v += __shfl_xor(v, 8, 64); v += __shfl_xor(v, 4, 64); v += __shfl_xor(v, 2, 64); v += __shfl_xor(v, 1, 64); } while (0)
; DI void phase5(const Params& p, char* lds0) {
;     ...
; #pragma unroll
;       for (int e = 0; e < 8; ++e) {
;         const float* wr = wg + (4 + g * 8 + e) * 1024;
;         float a = 0.f;
; #pragma unroll
;         for (int j = 0; j < 8; ++j) {
;           float4 wv = *(const float4*)(wr + j * 128 + l32 * 4);
;           a += hv[j * 4 + 0] * wv.x + hv[j * 4 + 1] * wv.y + hv[j * 4 + 2] * wv.z + hv[j * 4 + 3] * wv.w;
;         }
;         HSUM(a);
;         le[e] = a + p.b_re[g * 8 + e];
;       }
	v_mul_f32_e32 v172, v91, v189
	v_fmac_f32_e32 v172, v90, v188
	v_fmac_f32_e32 v172, v92, v190
	v_fmac_f32_e32 v172, v93, v191
	ds_read_b128 v[188:191], v170 offset:34816
	v_add_f32_e32 v171, v171, v172
	s_waitcnt lgkmcnt(1)
	v_mul_f32_e32 v172, v97, v193
	v_fmac_f32_e32 v172, v96, v192
	v_fmac_f32_e32 v172, v88, v194
	v_fmac_f32_e32 v172, v89, v195
	ds_read_b128 v[192:195], v170 offset:35328
	v_pk_add_f32 v[76:77], v[76:77], v[84:85]
	v_add_f32_e32 v171, v171, v172
	s_waitcnt lgkmcnt(1)
	v_mul_f32_e32 v172, v81, v189
	ds_bpermute_b32 v84, v176, v76
	ds_bpermute_b32 v85, v176, v77
	v_fmac_f32_e32 v172, v80, v188
	v_fmac_f32_e32 v172, v86, v190
	v_fmac_f32_e32 v172, v87, v191
	ds_read_b128 v[188:191], v170 offset:35840
	v_add_f32_e32 v171, v171, v172
	s_waitcnt lgkmcnt(3)
	v_mul_f32_e32 v172, v83, v193
	v_fmac_f32_e32 v172, v82, v192
	s_waitcnt lgkmcnt(1)
	v_pk_add_f32 v[76:77], v[76:77], v[84:85]
	v_fmac_f32_e32 v172, v78, v194
	ds_bpermute_b32 v84, v177, v76
	ds_bpermute_b32 v85, v177, v77
	v_fmac_f32_e32 v172, v79, v195
	ds_read_b128 v[192:195], v170 offset:36352
	v_add_f32_e32 v171, v171, v172
	s_waitcnt lgkmcnt(3)
	v_mul_f32_e32 v172, v71, v189
	v_fmac_f32_e32 v172, v70, v188
	v_fmac_f32_e32 v172, v72, v190
	v_fmac_f32_e32 v172, v73, v191
	s_waitcnt lgkmcnt(1)
	v_pk_add_f32 v[76:77], v[76:77], v[84:85]
	v_add_f32_e32 v171, v171, v172
	s_waitcnt lgkmcnt(0)
	v_mul_f32_e32 v172, v69, v193
	ds_bpermute_b32 v84, v178, v76
	ds_bpermute_b32 v85, v178, v77
	v_fmac_f32_e32 v172, v68, v192
	v_fmac_f32_e32 v172, v66, v194
	v_fmac_f32_e32 v172, v67, v195
	v_add_f32_e32 v171, v171, v172
	ds_bpermute_b32 v172, v176, v171
	s_waitcnt lgkmcnt(1)
	v_pk_add_f32 v[76:77], v[76:77], v[84:85]
	ds_bpermute_b32 v84, v179, v76
	ds_bpermute_b32 v85, v179, v77
	ds_read_b128 v[188:191], v170 offset:36864
	s_waitcnt lgkmcnt(3)
	v_add_f32_e32 v171, v171, v172
	ds_bpermute_b32 v172, v177, v171
	ds_read_b128 v[192:195], v170 offset:37376
	s_waitcnt lgkmcnt(3)
	v_pk_add_f32 v[76:77], v[76:77], v[84:85]
	s_waitcnt lgkmcnt(2)
	v_mul_f32_e32 v84, v161, v189
	v_fmac_f32_e32 v84, v160, v188
	v_fmac_f32_e32 v84, v162, v190
	v_fmac_f32_e32 v84, v163, v191
	ds_read_b128 v[188:191], v170 offset:37888
	s_waitcnt lgkmcnt(2)
	v_add_f32_e32 v85, v171, v172
	s_waitcnt lgkmcnt(1)
	v_mul_f32_e32 v171, v165, v193
	v_fmac_f32_e32 v171, v164, v192
	v_fmac_f32_e32 v171, v94, v194
	v_add_f32_e32 v84, 0, v84
	v_fmac_f32_e32 v171, v95, v195
	ds_read_b128 v[192:195], v170 offset:38400
	v_add_f32_e32 v84, v84, v171
	s_waitcnt lgkmcnt(1)
	v_mul_f32_e32 v171, v91, v189
	v_fmac_f32_e32 v171, v90, v188
	v_fmac_f32_e32 v171, v92, v190
	v_fmac_f32_e32 v171, v93, v191
	ds_read_b128 v[188:191], v170 offset:38912
	v_add_f32_e32 v84, v84, v171
	s_waitcnt lgkmcnt(1)
	v_mul_f32_e32 v171, v97, v193
	v_fmac_f32_e32 v171, v96, v192
	v_fmac_f32_e32 v171, v88, v194
	v_fmac_f32_e32 v171, v89, v195
	ds_read_b128 v[192:195], v170 offset:39424
	v_add_f32_e32 v84, v84, v171
	s_waitcnt lgkmcnt(1)
	v_mul_f32_e32 v171, v81, v189
	v_fmac_f32_e32 v171, v80, v188
	v_fmac_f32_e32 v171, v86, v190
	v_fmac_f32_e32 v171, v87, v191
	ds_read_b128 v[188:191], v170 offset:39936
	v_add_f32_e32 v84, v84, v171
	s_waitcnt lgkmcnt(1)
	v_mul_f32_e32 v171, v83, v193
	v_fmac_f32_e32 v171, v82, v192
	v_fmac_f32_e32 v171, v78, v194
	v_fmac_f32_e32 v171, v79, v195
	ds_read_b128 v[192:195], v170 offset:40448
	v_add_f32_e32 v84, v84, v171
	s_waitcnt lgkmcnt(1)
	v_mul_f32_e32 v171, v71, v189
	v_fmac_f32_e32 v171, v70, v188
	v_fmac_f32_e32 v171, v72, v190
	v_fmac_f32_e32 v171, v73, v191
	ds_read_b128 v[188:191], v170 offset:40960
	v_add_f32_e32 v84, v84, v171
	s_waitcnt lgkmcnt(1)
	v_mul_f32_e32 v171, v69, v193
	v_fmac_f32_e32 v171, v68, v192
	v_fmac_f32_e32 v171, v66, v194
	v_fmac_f32_e32 v171, v67, v195
	ds_read_b128 v[192:195], v170 offset:41472
	s_waitcnt lgkmcnt(1)
	v_mul_f32_e32 v172, v161, v189
	v_fmac_f32_e32 v172, v160, v188
	v_fmac_f32_e32 v172, v162, v190
	v_fmac_f32_e32 v172, v163, v191
	ds_read_b128 v[188:191], v170 offset:41984
	s_waitcnt lgkmcnt(1)
	v_mul_f32_e32 v173, v165, v193
	v_fmac_f32_e32 v173, v164, v192
	v_fmac_f32_e32 v173, v94, v194
	v_add_f32_e32 v172, 0, v172
	v_fmac_f32_e32 v173, v95, v195
	ds_read_b128 v[192:195], v170 offset:42496
	v_add_f32_e32 v172, v172, v173
	s_waitcnt lgkmcnt(1)
	v_mul_f32_e32 v173, v91, v189
	v_fmac_f32_e32 v173, v90, v188
	v_fmac_f32_e32 v173, v92, v190
	v_fmac_f32_e32 v173, v93, v191
	ds_read_b128 v[188:191], v170 offset:43008
	v_add_f32_e32 v172, v172, v173
	s_waitcnt lgkmcnt(1)
	v_mul_f32_e32 v173, v97, v193
	v_fmac_f32_e32 v173, v96, v192
	v_fmac_f32_e32 v173, v88, v194
	v_fmac_f32_e32 v173, v89, v195
	ds_read_b128 v[192:195], v170 offset:43520
	v_add_f32_e32 v172, v172, v173
	s_waitcnt lgkmcnt(1)
	v_mul_f32_e32 v173, v81, v189
	v_fmac_f32_e32 v173, v80, v188
	v_fmac_f32_e32 v173, v86, v190
	v_fmac_f32_e32 v173, v87, v191
	ds_read_b128 v[188:191], v170 offset:44032
	v_add_f32_e32 v172, v172, v173
	s_waitcnt lgkmcnt(1)
	v_mul_f32_e32 v173, v83, v193
	v_fmac_f32_e32 v173, v82, v192
	v_fmac_f32_e32 v173, v78, v194
	v_fmac_f32_e32 v173, v79, v195
	ds_read_b128 v[192:195], v170 offset:44544
	v_add_f32_e32 v172, v172, v173
	s_waitcnt lgkmcnt(1)
	v_mul_f32_e32 v173, v71, v189
	v_fmac_f32_e32 v173, v70, v188
	v_fmac_f32_e32 v173, v72, v190
	v_fmac_f32_e32 v173, v73, v191
	v_add_f32_e32 v172, v172, v173
	s_waitcnt lgkmcnt(0)
	v_mul_f32_e32 v173, v69, v193
	v_fmac_f32_e32 v173, v68, v192
	v_fmac_f32_e32 v173, v66, v194
	v_fmac_f32_e32 v173, v67, v195
	v_add_f32_e32 v84, v84, v171
	v_add_f32_e32 v172, v172, v173
	ds_bpermute_b32 v171, v176, v84
	ds_bpermute_b32 v173, v176, v172
	ds_bpermute_b32 v188, v178, v85
	ds_read_b128 v[192:195], v170 offset:45056
	s_waitcnt lgkmcnt(3)
; #define HSUM(v) do { v += __shfl_xor(v, 16, 64); v += __shfl_xor(v, 8, 64); v += __shfl_xor(v, 4, 64); v += __shfl_xor(v, 2, 64); v += __shfl_xor(v, 1, 64); } while (0)
; DI void phase5(const Params& p, char* lds0) {
;     ...
; #pragma unroll
;       for (int e = 0; e < 8; ++e) {
;         const float* wr = wg + (4 + g * 8 + e) * 1024;
;         float a = 0.f;
; #pragma unroll
;         for (int j = 0; j < 8; ++j) {
;           float4 wv = *(const float4*)(wr + j * 128 + l32 * 4);
;           a += hv[j * 4 + 0] * wv.x + hv[j * 4 + 1] * wv.y + hv[j * 4 + 2] * wv.z + hv[j * 4 + 3] * wv.w;
;         }
;         HSUM(a);
;         le[e] = a + p.b_re[g * 8 + e];
;       }
	v_add_f32_e32 v171, v84, v171
	s_waitcnt lgkmcnt(2)
	v_add_f32_e32 v172, v172, v173
	ds_bpermute_b32 v189, v177, v171
	ds_bpermute_b32 v173, v177, v172
	s_waitcnt lgkmcnt(3)
	v_add_f32_e32 v188, v85, v188
	ds_bpermute_b32 v190, v179, v188
	ds_bpermute_b32 v84, v180, v76
	s_waitcnt lgkmcnt(3)
	v_add_f32_e32 v171, v171, v189
	s_waitcnt lgkmcnt(2)
	v_add_f32_e32 v172, v172, v173
	ds_bpermute_b32 v189, v178, v171
	ds_bpermute_b32 v173, v178, v172
	ds_bpermute_b32 v85, v180, v77
	s_waitcnt lgkmcnt(2)
	v_add_f32_e32 v189, v171, v189
	v_add_f32_e32 v171, v188, v190
	s_waitcnt lgkmcnt(1)
	v_add_f32_e32 v190, v172, v173
	ds_bpermute_b32 v191, v179, v189
	ds_bpermute_b32 v196, v179, v190
	ds_bpermute_b32 v172, v180, v171
	s_waitcnt lgkmcnt(2)
	v_add_f32_e32 v173, v189, v191
	s_waitcnt lgkmcnt(1)
	v_add_f32_e32 v189, v190, v196
	ds_read_b128 v[196:199], v170 offset:45568
	v_mul_f32_e32 v191, v161, v193
	v_fmac_f32_e32 v191, v160, v192
	v_fmac_f32_e32 v191, v162, v194
	v_fmac_f32_e32 v191, v163, v195
	s_waitcnt lgkmcnt(0)
	v_mul_f32_e32 v197, v165, v197
	v_fmac_f32_e32 v197, v164, v196
	ds_read_b128 v[192:195], v170 offset:46080
	v_fmac_f32_e32 v197, v94, v198
	v_add_f32_e32 v191, 0, v191
	v_fmac_f32_e32 v197, v95, v199
	v_add_f32_e32 v191, v191, v197
	ds_read_b128 v[196:199], v170 offset:46592
	s_waitcnt lgkmcnt(1)
	v_mul_f32_e32 v193, v91, v193
	v_fmac_f32_e32 v193, v90, v192
	v_fmac_f32_e32 v193, v92, v194
	v_fmac_f32_e32 v193, v93, v195
	s_waitcnt lgkmcnt(0)
	v_mul_f32_e32 v197, v97, v197
	v_add_f32_e32 v191, v191, v193
	v_fmac_f32_e32 v197, v96, v196
	ds_read_b128 v[192:195], v170 offset:47104
	v_fmac_f32_e32 v197, v88, v198
	v_fmac_f32_e32 v197, v89, v199
	v_add_f32_e32 v191, v191, v197
	ds_read_b128 v[196:199], v170 offset:47616
	s_waitcnt lgkmcnt(1)
	v_mul_f32_e32 v193, v81, v193
	v_fmac_f32_e32 v193, v80, v192
	v_fmac_f32_e32 v193, v86, v194
	v_fmac_f32_e32 v193, v87, v195
	s_waitcnt lgkmcnt(0)
	v_mul_f32_e32 v197, v83, v197
	v_add_f32_e32 v191, v191, v193
	v_fmac_f32_e32 v197, v82, v196
	ds_read_b128 v[192:195], v170 offset:48128
	v_fmac_f32_e32 v197, v78, v198
	v_fmac_f32_e32 v197, v79, v199
	v_add_f32_e32 v191, v191, v197
	ds_read_b128 v[196:199], v170 offset:48640
	s_waitcnt lgkmcnt(1)
	v_mul_f32_e32 v193, v71, v193
	v_fmac_f32_e32 v193, v70, v192
	v_fmac_f32_e32 v193, v72, v194
	v_fmac_f32_e32 v193, v73, v195
	s_waitcnt lgkmcnt(0)
	v_mul_f32_e32 v197, v69, v197
	v_add_f32_e32 v191, v191, v193
	v_fmac_f32_e32 v197, v68, v196
	ds_read_b128 v[192:195], v170 offset:49152
	v_fmac_f32_e32 v197, v66, v198
	v_fmac_f32_e32 v197, v67, v199
	v_add_f32_e32 v191, v191, v197
	ds_read_b128 v[196:199], v170 offset:49664
	s_waitcnt lgkmcnt(1)
	v_mul_f32_e32 v193, v161, v193
	v_fmac_f32_e32 v193, v160, v192
	v_fmac_f32_e32 v193, v162, v194
	v_fmac_f32_e32 v193, v163, v195
	s_waitcnt lgkmcnt(0)
	v_mul_f32_e32 v197, v165, v197
	v_add_f32_e32 v201, 0, v193
	v_fmac_f32_e32 v197, v164, v196
	ds_read_b128 v[192:195], v170 offset:50176
	v_fmac_f32_e32 v197, v94, v198
	v_fmac_f32_e32 v197, v95, v199
	v_add_f32_e32 v201, v201, v197
	ds_read_b128 v[196:199], v170 offset:50688
	s_waitcnt lgkmcnt(1)
	v_mul_f32_e32 v193, v91, v193
	v_fmac_f32_e32 v193, v90, v192
	v_fmac_f32_e32 v193, v92, v194
	v_fmac_f32_e32 v193, v93, v195
	s_waitcnt lgkmcnt(0)
	v_mul_f32_e32 v197, v97, v197
	v_add_f32_e32 v201, v201, v193
	v_fmac_f32_e32 v197, v96, v196
	ds_read_b128 v[192:195], v170 offset:51200
	v_fmac_f32_e32 v197, v88, v198
	v_fmac_f32_e32 v197, v89, v199
	v_add_f32_e32 v201, v201, v197
	ds_read_b128 v[196:199], v170 offset:51712
	s_waitcnt lgkmcnt(1)
	v_mul_f32_e32 v193, v81, v193
	v_fmac_f32_e32 v193, v80, v192
	v_fmac_f32_e32 v193, v86, v194
	v_fmac_f32_e32 v193, v87, v195
	s_waitcnt lgkmcnt(0)
	v_mul_f32_e32 v197, v83, v197
	v_add_f32_e32 v201, v201, v193
	v_fmac_f32_e32 v197, v82, v196
	ds_read_b128 v[192:195], v170 offset:52224
	v_fmac_f32_e32 v197, v78, v198
	v_fmac_f32_e32 v197, v79, v199
	v_add_f32_e32 v201, v201, v197
	ds_read_b128 v[196:199], v170 offset:52736
	s_waitcnt lgkmcnt(1)
	v_mul_f32_e32 v193, v71, v193
	v_fmac_f32_e32 v193, v70, v192
	v_fmac_f32_e32 v193, v72, v194
	v_fmac_f32_e32 v193, v73, v195
	s_waitcnt lgkmcnt(0)
	v_mul_f32_e32 v197, v69, v197
	v_add_f32_e32 v201, v201, v193
	v_fmac_f32_e32 v197, v68, v196
	ds_read_b128 v[192:195], v170 offset:53248
	v_fmac_f32_e32 v197, v66, v198
	v_fmac_f32_e32 v197, v67, v199
	v_add_f32_e32 v201, v201, v197
	ds_read_b128 v[196:199], v170 offset:53760
	s_waitcnt lgkmcnt(1)
	v_mul_f32_e32 v161, v161, v193
	v_fmac_f32_e32 v161, v160, v192
	v_fmac_f32_e32 v161, v162, v194
	v_fmac_f32_e32 v161, v163, v195
	s_waitcnt lgkmcnt(0)
	v_mul_f32_e32 v165, v165, v197
	v_add_f32_e32 v192, 0, v161
	v_fmac_f32_e32 v165, v164, v196
	ds_read_b128 v[160:163], v170 offset:54272
	v_fmac_f32_e32 v165, v94, v198
	v_fmac_f32_e32 v165, v95, v199
	v_add_f32_e32 v94, v192, v165
	ds_read_b128 v[192:195], v170 offset:54784
	s_waitcnt lgkmcnt(1)
	v_mul_f32_e32 v91, v91, v161
	v_fmac_f32_e32 v91, v90, v160
	v_fmac_f32_e32 v91, v92, v162
	v_fmac_f32_e32 v91, v93, v163
	s_waitcnt lgkmcnt(0)
	v_mul_f32_e32 v95, v97, v193
	v_add_f32_e32 v94, v94, v91
	v_fmac_f32_e32 v95, v96, v192
	ds_read_b128 v[90:93], v170 offset:55296
	v_fmac_f32_e32 v95, v88, v194
	v_fmac_f32_e32 v95, v89, v195
	v_add_f32_e32 v88, v94, v95
	ds_read_b128 v[94:97], v170 offset:55808
	s_waitcnt lgkmcnt(1)
	v_mul_f32_e32 v81, v81, v91
	v_fmac_f32_e32 v81, v80, v90
	v_fmac_f32_e32 v81, v86, v92
	v_fmac_f32_e32 v81, v87, v93
	s_waitcnt lgkmcnt(0)
; #define HSUM(v) do { v += __shfl_xor(v, 16, 64); v += __shfl_xor(v, 8, 64); v += __shfl_xor(v, 4, 64); v += __shfl_xor(v, 2, 64); v += __shfl_xor(v, 1, 64); } while (0)
; DI void phase5(const Params& p, char* lds0) {
;     ...
;         HSUM(a);
;         le[e] = a + p.b_re[g * 8 + e];
;       }
;     ...
;       int i1 = 0; float v1 = le[0];
; #pragma unroll
;       for (int e = 1; e < 8; ++e) if (le[e] > v1) { v1 = le[e]; i1 = e; }
;       int i2 = -1; float v2 = -3.0e38f;
; #pragma unroll
;       for (int e = 0; e < 8; ++e) if (e != i1 && le[e] > v2) { v2 = le[e]; i2 = e; }
;       const float e2 = __expf(v2 - v1);
;       const float w1 = pgrp / (1.f + e2), w2 = pgrp * e2 / (1.f + e2);
;       if (l32 == 0) {
;         const int li0 = (g * 8 + i1) * 2, li1 = (g * 8 + i2) * 2 + 1;
;         const int lp0 = atomicAdd(&hist[li0], 1), lp1 = atomicAdd(&hist[li1], 1);
;         info[tl * 4 + 0] = li0; info[tl * 4 + 1] = li1; info[tl * 4 + 2] = lp0; info[tl * 4 + 3] = lp1;
;         gate[t] = w1; gate[T + t] = w2;
;       }
	v_mul_f32_e32 v87, v83, v95
	v_fmac_f32_e32 v87, v82, v94
	v_fmac_f32_e32 v87, v78, v96
	v_add_f32_e32 v86, v88, v81
	ds_read_b128 v[80:83], v170 offset:56320
	v_fmac_f32_e32 v87, v79, v97
	v_add_f32_e32 v78, v86, v87
	ds_read_b128 v[86:89], v170 offset:56832
	ds_bpermute_b32 v200, v176, v191
	s_waitcnt lgkmcnt(2)
	v_mul_f32_e32 v71, v71, v81
	v_fmac_f32_e32 v71, v70, v80
	v_fmac_f32_e32 v71, v72, v82
	s_waitcnt lgkmcnt(1)
	v_mul_f32_e32 v69, v69, v87
	v_fmac_f32_e32 v69, v68, v86
	v_fmac_f32_e32 v71, v73, v83
	v_fmac_f32_e32 v69, v66, v88
	v_add_f32_e32 v70, v78, v71
	v_fmac_f32_e32 v69, v67, v89
	v_add_f32_e32 v66, v70, v69
	ds_bpermute_b32 v202, v176, v201
	ds_bpermute_b32 v67, v176, v66
	s_waitcnt lgkmcnt(2)
	v_add_f32_e32 v68, v191, v200
	ds_bpermute_b32 v69, v177, v68
	ds_bpermute_b32 v188, v180, v173
	s_waitcnt lgkmcnt(3)
	v_add_f32_e32 v70, v201, v202
	s_waitcnt lgkmcnt(2)
	v_add_f32_e32 v66, v66, v67
	ds_bpermute_b32 v71, v177, v70
	ds_bpermute_b32 v67, v177, v66
	s_waitcnt lgkmcnt(3)
	v_add_f32_e32 v68, v68, v69
	ds_bpermute_b32 v69, v178, v68
	ds_bpermute_b32 v190, v180, v189
	s_waitcnt lgkmcnt(3)
	v_add_f32_e32 v70, v70, v71
	s_waitcnt lgkmcnt(2)
	v_add_f32_e32 v66, v66, v67
	ds_bpermute_b32 v71, v178, v70
	ds_bpermute_b32 v67, v178, v66
	s_waitcnt lgkmcnt(3)
	v_add_f32_e32 v68, v68, v69
	ds_bpermute_b32 v69, v179, v68
	s_waitcnt lgkmcnt(2)
	v_add_f32_e32 v70, v70, v71
	s_waitcnt lgkmcnt(1)
	v_add_f32_e32 v72, v66, v67
	ds_bpermute_b32 v71, v179, v70
	ds_bpermute_b32 v73, v179, v72
	s_waitcnt lgkmcnt(2)
	v_add_f32_e32 v66, v68, v69
	ds_bpermute_b32 v67, v180, v66
	s_waitcnt lgkmcnt(2)
	v_add_f32_e32 v68, v70, v71
	s_waitcnt lgkmcnt(1)
	v_add_f32_e32 v70, v72, v73
	ds_bpermute_b32 v69, v180, v68
	ds_bpermute_b32 v71, v180, v70
	s_and_saveexec_b64 s[38:39], s[4:5]
	s_cbranch_execz .LBB0_255
	v_lshlrev_b32_e32 v72, 2, v166
	global_load_dwordx4 v[78:81], v72, s[30:31] offset:16
	global_load_dwordx4 v[86:89], v72, s[30:31]
	s_waitcnt lgkmcnt(1)
	v_add_f32_e32 v68, v68, v69
	v_add_f32_e32 v69, v66, v67
	v_cndmask_b32_e32 v66, v169, v167, vcc
	v_sub_f32_e32 v67, v74, v66
	v_sub_f32_e32 v74, v75, v66
	v_mul_f32_e32 v67, 0x3fb8aa3b, v67
	v_sub_f32_e32 v75, v168, v66
	v_mul_f32_e32 v74, 0x3fb8aa3b, v74
	v_exp_f32_e32 v67, v67
	v_sub_f32_e32 v66, v167, v66
	v_mul_f32_e32 v75, 0x3fb8aa3b, v75
	v_exp_f32_e32 v74, v74
	v_mul_f32_e32 v66, 0x3fb8aa3b, v66
	v_exp_f32_e32 v75, v75
	v_exp_f32_e32 v66, v66
	v_add_f32_e32 v67, 0, v67
	v_add_f32_e32 v67, v74, v67
	v_add_f32_e32 v67, v75, v67
	v_add_f32_e32 v74, v66, v67
	v_div_scale_f32 v75, s[6:7], v74, v74, 1.0
	v_rcp_f32_e32 v82, v75
	v_pk_add_f32 v[66:67], v[76:77], v[84:85]
	v_div_scale_f32 v76, vcc, 1.0, v74, 1.0
	v_fma_f32 v77, -v75, v82, 1.0
	v_fmac_f32_e32 v82, v77, v82
	v_mul_f32_e32 v77, v76, v82
	v_fma_f32 v83, -v75, v77, v76
	v_fmac_f32_e32 v77, v83, v82
	v_fma_f32 v75, -v75, v77, v76
	v_add_f32_e32 v73, v171, v172
	v_div_fmas_f32 v75, v75, v82, v77
	v_div_fixup_f32 v74, v75, v74, 1.0
	v_add_f32_e32 v72, v173, v188
	s_waitcnt lgkmcnt(0)
	v_add_f32_e32 v70, v70, v71
	v_add_f32_e32 v71, v189, v190
	s_waitcnt vmcnt(1)
	v_add_f32_e32 v71, v71, v78
	s_waitcnt vmcnt(0)
	v_pk_add_f32 v[66:67], v[66:67], v[86:87]
	v_add_f32_e32 v73, v73, v88
	v_cmp_gt_f32_e32 vcc, v67, v66
	v_add_f32_e32 v72, v72, v89
	v_add_f32_e32 v69, v69, v79
	v_cndmask_b32_e32 v75, v66, v67, vcc
	v_cmp_gt_f32_e64 s[8:9], v73, v75
	v_cndmask_b32_e64 v76, 0, 1, vcc
	v_add_f32_e32 v68, v68, v80
	v_cndmask_b32_e64 v75, v75, v73, s[8:9]
	v_cmp_gt_f32_e32 vcc, v72, v75
	v_cndmask_b32_e64 v76, v76, 2, s[8:9]
	v_add_f32_e32 v70, v70, v81
	v_cndmask_b32_e32 v75, v75, v72, vcc
	v_cmp_gt_f32_e64 s[8:9], v71, v75
	v_cndmask_b32_e64 v76, v76, 3, vcc
	v_cmp_nlt_f32_e64 s[6:7], s41, v66
	v_cndmask_b32_e64 v75, v75, v71, s[8:9]
	v_cmp_gt_f32_e32 vcc, v69, v75
	v_cndmask_b32_e64 v76, v76, 4, s[8:9]
	s_nop 0
	v_cndmask_b32_e32 v75, v75, v69, vcc
	v_cmp_gt_f32_e64 s[8:9], v68, v75
	v_cndmask_b32_e64 v76, v76, 5, vcc
	s_nop 0
	v_cndmask_b32_e64 v75, v75, v68, s[8:9]
	v_cndmask_b32_e64 v76, v76, 6, s[8:9]
	v_cmp_ngt_f32_e32 vcc, v70, v75
	s_and_b64 s[46:47], s[8:9], vcc
	s_nop 0
	v_cndmask_b32_e32 v76, 7, v76, vcc
	v_cmp_eq_u32_e64 s[18:19], 0, v76
	s_or_b64 s[6:7], s[18:19], s[6:7]
	v_cndmask_b32_e64 v66, v66, v185, s[6:7]
	v_cmp_ne_u32_e64 s[16:17], 1, v76
	v_cmp_gt_f32_e64 s[18:19], v67, v66
	v_cndmask_b32_e64 v77, 0, -1, s[6:7]
	s_and_b64 s[6:7], s[16:17], s[18:19]
	v_cndmask_b32_e64 v66, v66, v67, s[6:7]
	v_cmp_ne_u32_e64 s[14:15], 2, v76
	v_cmp_gt_f32_e64 s[16:17], v73, v66
	v_cndmask_b32_e64 v67, v77, 1, s[6:7]
	s_and_b64 s[6:7], s[14:15], s[16:17]
	v_cndmask_b32_e64 v66, v66, v73, s[6:7]
	v_cmp_ne_u32_e64 s[12:13], 3, v76
	v_cmp_gt_f32_e64 s[14:15], v72, v66
	v_cndmask_b32_e64 v67, v67, 2, s[6:7]
	s_and_b64 s[6:7], s[12:13], s[14:15]
	v_cndmask_b32_e64 v66, v66, v72, s[6:7]
	v_cmp_ne_u32_e64 s[10:11], 4, v76
	v_cmp_gt_f32_e64 s[12:13], v71, v66
	v_cndmask_b32_e64 v67, v67, 3, s[6:7]
	s_and_b64 s[6:7], s[10:11], s[12:13]
	v_cndmask_b32_e64 v66, v66, v71, s[6:7]
	v_cmp_ne_u32_e64 s[8:9], 5, v76
	v_cmp_gt_f32_e64 s[10:11], v69, v66
	s_and_b64 s[8:9], s[8:9], s[10:11]
	v_cndmask_b32_e64 v66, v66, v69, s[8:9]
	v_cmp_ngt_f32_e64 s[10:11], v68, v66
	s_or_b64 s[10:11], s[46:47], s[10:11]
	v_cndmask_b32_e32 v75, v70, v75, vcc
	v_cndmask_b32_e64 v66, v68, v66, s[10:11]
	v_cmp_gt_f32_e64 s[12:13], v70, v66
	s_and_b64 vcc, vcc, s[12:13]
	v_cndmask_b32_e32 v66, v66, v70, vcc
	v_sub_f32_e32 v66, v66, v75
	v_mul_f32_e32 v66, 0x3fb8aa3b, v66
	v_exp_f32_e32 v66, v66
	v_cndmask_b32_e64 v67, v67, 4, s[6:7]
	v_cndmask_b32_e64 v67, v67, 5, s[8:9]
	v_cndmask_b32_e64 v67, 6, v67, s[10:11]
	v_mul_f32_e32 v68, v74, v66
	v_add_f32_e32 v66, 1.0, v66
	v_cndmask_b32_e64 v67, v67, 7, vcc
	v_rcp_f32_e32 v69, v66
	v_or_b32_e32 v75, v76, v166
	v_mul_f32_e32 v70, v68, v69
	v_add_u32_e32 v67, v67, v166
	v_lshl_add_u32 v68, v75, 3, v1
	ds_add_rtn_u32 v68, v68, v183
	v_lshl_add_u32 v69, v67, 3, v1
	ds_add_rtn_u32 v69, v69, v183 offset:4
	v_rcp_f32_e32 v71, v66
	s_nop 0
	v_mul_f32_e32 v71, v74, v71
	v_lshlrev_b32_e32 v66, 1, v75
	v_lshl_or_b32 v67, v67, 1, 1
	s_waitcnt lgkmcnt(0)
	ds_write_b128 v187, v[66:69]
	v_lshl_add_u64 v[66:67], v[158:159], 2, s[22:23]
	global_store_dword v[66:67], v71, off
	v_add_co_u32_e32 v66, vcc, 0x60000, v66
	s_nop 1
	v_addc_co_u32_e32 v67, vcc, 0, v67, vcc
	global_store_dword v[66:67], v70, off
	s_branch .LBB0_255

; #define MFMA(a, b, c) __builtin_amdgcn_mfma_f32_32x32x16_bf16((a), (b), (c), 0, 0, 0)
; #define WAIT_V(n) asm volatile("s_waitcnt vmcnt(%0)" ::"n"(n) : "memory")
; #define RAW_BARRIER() do { asm volatile("s_waitcnt lgkmcnt(0)" ::: "memory"); __builtin_amdgcn_s_barrier(); } while (0)
; template <typename FA, typename FB, typename FE>
; DI void gemm_tile(char* lds, int K, int astride, int bstride, FA arow, FB brow, FE epi) {
;     ...
;   stage(0, 0); stage(1, 1); stage(2, 2);
;   for (int kt = 0; kt < nk; ++kt) {
;     if (kt + 2 < nk) WAIT_V(8); else if (kt + 1 < nk) WAIT_V(4); else WAIT_V(0);
;     RAW_BARRIER();
;     if (kt + 3 < nk) stage((kt + 3) & 3, kt + 3);
;     const char* sa = lds + (kt & 3) * 32768 + wm * 4096;
;     const char* sb = lds + (kt & 3) * 32768 + 16384 + wn * 8192;
; #pragma unroll
;     for (int ks = 0; ks < 2; ++ks) {
;       bf16x8 a0 = *(const bf16x8*)(sa + foff[ks]), a1 = *(const bf16x8*)(sa + 2048 + foff[ks]);
; #pragma unroll
;       for (int nt = 0; nt < 4; ++nt) {
;         bf16x8 bb = *(const bf16x8*)(sb + nt * 2048 + foff[ks]);
;         acc[0][nt] = MFMA(a0, bb, acc[0][nt]);
;         acc[1][nt] = MFMA(a1, bb, acc[1][nt]);
;       }
;     }
;   }
.Lgm_P6_loop:
	s_and_b32 s25, s24, 0x18000
	s_add_i32 s25, s41, s25
	s_waitcnt vmcnt(4)
	v_lshl_add_u64 v[138:139], v[134:135], 0, v[150:151]
	v_lshl_add_u64 v[140:141], v[130:131], 0, v[150:151]
	s_mov_b32 m0, s25
	s_barrier
	s_add_i32 s42, s24, 0xfffe8000
	s_and_b32 s42, s42, 0x18000
	s_add_i32 s43, s42, s40
	s_or_b32 s42, s42, s27
	v_add_u32_e32 v246, s43, v160
	v_add_u32_e32 v247, s42, v160
	s_waitcnt lgkmcnt(4)
	v_mfma_f32_32x32x16_bf16 v[114:129], v[196:199], v[204:207], v[114:129]
	global_load_lds_dwordx4 v[138:139], off
	s_add_i32 m0, s25, 0x4000
	ds_read_b128 v[220:223], v246
	s_waitcnt lgkmcnt(4)
	v_mfma_f32_32x32x16_bf16 v[50:65], v[200:203], v[204:207], v[50:65]
	v_lshl_add_u64 v[142:143], v[136:137], 0, v[150:151]
	global_load_lds_dwordx4 v[140:141], off
	s_add_i32 m0, s25, 0x400
	ds_read_b128 v[228:231], v247 offset:16384
	s_waitcnt lgkmcnt(4)
	v_mfma_f32_32x32x16_bf16 v[98:113], v[196:199], v[208:211], v[98:113]
	v_lshl_add_u64 v[144:145], v[132:133], 0, v[150:151]
	global_load_lds_dwordx4 v[142:143], off
	s_add_i32 m0, s25, 0x4400
	ds_read_b128 v[224:227], v246 offset:2048
	v_mfma_f32_32x32x16_bf16 v[34:49], v[200:203], v[208:211], v[34:49]
	ds_read_b128 v[232:235], v247 offset:18432
	global_load_lds_dwordx4 v[144:145], off
	s_waitcnt lgkmcnt(5)
	v_mfma_f32_32x32x16_bf16 v[82:97], v[196:199], v[212:215], v[82:97]
	ds_read_b128 v[236:239], v247 offset:20480
	v_lshl_add_u64 v[130:131], v[130:131], 0, s[18:19]
	v_lshl_add_u64 v[132:133], v[132:133], 0, s[18:19]
	v_mfma_f32_32x32x16_bf16 v[18:33], v[200:203], v[212:215], v[18:33]
	ds_read_b128 v[240:243], v247 offset:22528
	v_lshl_add_u64 v[134:135], v[134:135], 0, 64
	v_lshl_add_u64 v[136:137], v[136:137], 0, 64
	s_waitcnt lgkmcnt(6)
	v_mfma_f32_32x32x16_bf16 v[66:81], v[196:199], v[216:219], v[66:81]
	s_add_i32 s42, s24, 0xffff0000
	s_and_b32 s42, s42, 0x18000
	s_add_i32 s43, s42, s40
	v_mfma_f32_32x32x16_bf16 v[2:17], v[200:203], v[216:219], v[2:17]
	s_or_b32 s42, s42, s27
	v_add_u32_e32 v244, s43, v159
	v_add_u32_e32 v245, s42, v159
	s_waitcnt lgkmcnt(4)
	v_mfma_f32_32x32x16_bf16 v[114:129], v[220:223], v[228:231], v[114:129]
	ds_read_b128 v[196:199], v244
	s_waitcnt lgkmcnt(4)
	v_mfma_f32_32x32x16_bf16 v[50:65], v[224:227], v[228:231], v[50:65]
	ds_read_b128 v[204:207], v245 offset:16384
	s_waitcnt lgkmcnt(4)
	v_mfma_f32_32x32x16_bf16 v[98:113], v[220:223], v[232:235], v[98:113]
	ds_read_b128 v[200:203], v244 offset:2048
	v_mfma_f32_32x32x16_bf16 v[34:49], v[224:227], v[232:235], v[34:49]
	ds_read_b128 v[208:211], v245 offset:18432
	s_waitcnt lgkmcnt(5)
	v_mfma_f32_32x32x16_bf16 v[82:97], v[220:223], v[236:239], v[82:97]
	ds_read_b128 v[212:215], v245 offset:20480
	v_mfma_f32_32x32x16_bf16 v[18:33], v[224:227], v[236:239], v[18:33]
	ds_read_b128 v[216:219], v245 offset:22528
	s_waitcnt lgkmcnt(6)
	v_mfma_f32_32x32x16_bf16 v[66:81], v[220:223], v[240:243], v[66:81]
	s_add_i32 s24, s24, 0x8000
	v_mfma_f32_32x32x16_bf16 v[2:17], v[224:227], v[240:243], v[2:17]
	s_cmp_eq_u32 s24, 0x100000
	s_cbranch_scc0 .Lgm_P6_loop
	s_waitcnt vmcnt(8)
	v_add_u32_e32 v138, s40, v159
	s_waitcnt lgkmcnt(0)
	s_barrier
	ds_read_b128 v[130:133], v138 offset:32768
	ds_read_b128 v[138:141], v138 offset:34816
	v_add_u32_e32 v142, s27, v159
	ds_read_b128 v[134:137], v142 offset:49152
	v_add_u32_e32 v143, s27, v160
	s_add_i32 s24, s40, 0x10000
	s_waitcnt lgkmcnt(0)
	v_mfma_f32_32x32x16_bf16 v[114:129], v[130:133], v[134:137], v[114:129]
	s_or_b32 s25, s27, 0x14000
	v_add_u32_e32 v169, s25, v159
	v_add_u32_e32 v182, s24, v160
	v_mfma_f32_32x32x16_bf16 v[50:65], v[138:141], v[134:137], v[50:65]
	ds_read_b128 v[134:137], v142 offset:51200
	s_waitcnt lgkmcnt(0)
	v_mfma_f32_32x32x16_bf16 v[98:113], v[130:133], v[134:137], v[98:113]
	v_mfma_f32_32x32x16_bf16 v[34:49], v[138:141], v[134:137], v[34:49]
	ds_read_b128 v[134:137], v142 offset:53248
	s_waitcnt lgkmcnt(0)
	v_mfma_f32_32x32x16_bf16 v[82:97], v[130:133], v[134:137], v[82:97]
	v_mfma_f32_32x32x16_bf16 v[18:33], v[138:141], v[134:137], v[18:33]
	ds_read_b128 v[134:137], v142 offset:55296
	v_add_u32_e32 v142, s40, v160
	s_add_i32 s40, s40, 0x18000
	v_add_u32_e32 v202, s40, v160
	s_waitcnt lgkmcnt(0)
	v_mfma_f32_32x32x16_bf16 v[66:81], v[130:133], v[134:137], v[66:81]
	ds_read_b128 v[130:133], v142 offset:32768
	v_mfma_f32_32x32x16_bf16 v[2:17], v[138:141], v[134:137], v[2:17]
	ds_read_b128 v[138:141], v142 offset:34816
	ds_read_b128 v[134:137], v143 offset:49152
	v_add_u32_e32 v142, s24, v159
	s_or_b32 s24, s27, 0x1c000
	v_add_u32_e32 v234, s24, v159
	v_add_u32_e32 v226, s24, v160
	s_waitcnt lgkmcnt(0)
	v_mfma_f32_32x32x16_bf16 v[114:129], v[130:133], v[134:137], v[114:129]
	v_mfma_f32_32x32x16_bf16 v[50:65], v[138:141], v[134:137], v[50:65]
	ds_read_b128 v[134:137], v143 offset:51200
	s_waitcnt lgkmcnt(0)
	v_mfma_f32_32x32x16_bf16 v[98:113], v[130:133], v[134:137], v[98:113]
	v_mfma_f32_32x32x16_bf16 v[34:49], v[138:141], v[134:137], v[34:49]
	ds_read_b128 v[134:137], v143 offset:53248
	s_waitcnt lgkmcnt(0)
	v_mfma_f32_32x32x16_bf16 v[82:97], v[130:133], v[134:137], v[82:97]
	v_mfma_f32_32x32x16_bf16 v[18:33], v[138:141], v[134:137], v[18:33]
	ds_read_b128 v[134:137], v143 offset:55296
	s_waitcnt vmcnt(4)
	s_waitcnt lgkmcnt(0)
	s_barrier
; #define MFMA(a, b, c) __builtin_amdgcn_mfma_f32_32x32x16_bf16((a), (b), (c), 0, 0, 0)
; DI unsigned pk2(float a, float b) { fl2_t f = {a, b}; bf2_t r = __builtin_convertvector(f, bf2_t); return __builtin_bit_cast(unsigned, r); }
; #define WAIT_V(n) asm volatile("s_waitcnt vmcnt(%0)" ::"n"(n) : "memory")
; #define RAW_BARRIER() do { asm volatile("s_waitcnt lgkmcnt(0)" ::: "memory"); __builtin_amdgcn_s_barrier(); } while (0)
; template <typename FA, typename FB, typename FE>
; DI void gemm_tile(char* lds, int K, int astride, int bstride, FA arow, FB brow, FE epi) {
;     ...
;   for (int kt = 0; kt < nk; ++kt) {
;     if (kt + 2 < nk) WAIT_V(8); else if (kt + 1 < nk) WAIT_V(4); else WAIT_V(0);
;     RAW_BARRIER();
;     if (kt + 3 < nk) stage((kt + 3) & 3, kt + 3);
;     const char* sa = lds + (kt & 3) * 32768 + wm * 4096;
;     const char* sb = lds + (kt & 3) * 32768 + 16384 + wn * 8192;
; #pragma unroll
;     for (int ks = 0; ks < 2; ++ks) {
;       bf16x8 a0 = *(const bf16x8*)(sa + foff[ks]), a1 = *(const bf16x8*)(sa + 2048 + foff[ks]);
; #pragma unroll
;       for (int nt = 0; nt < 4; ++nt) {
;         bf16x8 bb = *(const bf16x8*)(sb + nt * 2048 + foff[ks]);
;         acc[0][nt] = MFMA(a0, bb, acc[0][nt]);
;         acc[1][nt] = MFMA(a1, bb, acc[1][nt]);
;       }
;     }
;   }
;   RAW_BARRIER();
;   bfr* Cs = (bfr*)lds;
; #pragma unroll
;   for (int mt = 0; mt < 2; ++mt)
; #pragma unroll
;     for (int nt = 0; nt < 4; ++nt)
; #pragma unroll
;       for (int i = 0; i < 16; i += 2) {
;         const int row = wm * 64 + mt * 32 + (i & 3) + 8 * (i >> 2) + 4 * h8;
;         const unsigned pr = pk2(acc[mt][nt][i], acc[mt][nt][i + 1]);
;         Cs[row * CSS + wn * 128 + nt * 32 + r] = (bfr)(pr & 0xffffu);
;         Cs[(row + 1) * CSS + wn * 128 + nt * 32 + r] = (bfr)(pr >> 16);
;       }
	ds_read_b128 v[170:173], v142
	s_waitcnt lgkmcnt(0)
	v_mfma_f32_32x32x16_bf16 v[66:81], v[130:133], v[134:137], v[66:81]
	ds_read_b128 v[130:133], v169
	v_mfma_f32_32x32x16_bf16 v[2:17], v[138:141], v[134:137], v[2:17]
	ds_read_b128 v[134:137], v142 offset:2048
	ds_read_b128 v[142:145], v169 offset:2048
	v_add_u32_e32 v138, s25, v160
	s_waitcnt lgkmcnt(0)
	v_mfma_f32_32x32x16_bf16 v[114:129], v[170:173], v[130:133], v[114:129]
	v_mfma_f32_32x32x16_bf16 v[50:65], v[134:137], v[130:133], v[50:65]
	ds_read_b128 v[130:133], v138 offset:6144
	ds_read_b128 v[146:149], v138 offset:4096
	ds_read_b128 v[174:177], v138 offset:2048
	ds_read_b128 v[178:181], v138
	ds_read_b128 v[138:141], v182 offset:2048
	ds_read_b128 v[182:185], v182
	v_mfma_f32_32x32x16_bf16 v[98:113], v[170:173], v[142:145], v[98:113]
	v_mfma_f32_32x32x16_bf16 v[34:49], v[134:137], v[142:145], v[34:49]
	ds_read_b128 v[142:145], v169 offset:6144
	ds_read_b128 v[186:189], v169 offset:4096
	s_waitcnt vmcnt(0)
	v_add_u32_e32 v169, s40, v159
	s_waitcnt lgkmcnt(0)
	s_barrier
	ds_read_b128 v[190:193], v169
	ds_read_b128 v[194:197], v234
	s_waitcnt lgkmcnt(0)
	v_mfma_f32_32x32x16_bf16 v[114:129], v[182:185], v[178:181], v[114:129]
	ds_read_b128 v[198:201], v202 offset:2048
	ds_read_b128 v[202:205], v202
	ds_read_b128 v[206:209], v226 offset:2048
	ds_read_b128 v[210:213], v226
	ds_read_b128 v[214:217], v234 offset:2048
	ds_read_b128 v[218:221], v169 offset:2048
	ds_read_b128 v[222:225], v226 offset:6144
	ds_read_b128 v[226:229], v226 offset:4096
	ds_read_b128 v[230:233], v234 offset:6144
	ds_read_b128 v[234:237], v234 offset:4096
	v_lshl_or_b32 v169, s16, 6, v161
	s_waitcnt lgkmcnt(0)
	s_barrier
	v_mfma_f32_32x32x16_bf16 v[82:97], v[170:173], v[186:189], v[82:97]
	v_mfma_f32_32x32x16_bf16 v[114:129], v[190:193], v[194:197], v[114:129]
	v_mfma_f32_32x32x16_bf16 v[98:113], v[182:185], v[174:177], v[98:113]
	v_mfma_f32_32x32x16_bf16 v[66:81], v[170:173], v[142:145], v[66:81]
	v_mfma_f32_32x32x16_bf16 v[82:97], v[182:185], v[146:149], v[82:97]
	s_waitcnt lgkmcnt(0)
	v_mfma_f32_32x32x16_bf16 v[114:129], v[202:205], v[210:213], v[114:129]
	v_mfma_f32_32x32x16_bf16 v[98:113], v[190:193], v[214:217], v[98:113]
	s_nop 10
	v_cvt_pk_bf16_f32 v238, v114, v115
	v_lshl_or_b32 v114, s26, 8, v165
	v_mad_u64_u32 v[114:115], s[24:25], v169, s35, v[114:115]
	v_cvt_pk_bf16_f32 v115, v116, v117
	ds_write_b16 v114, v238
	ds_write_b16_d16_hi v114, v238 offset:528
	ds_write_b16 v114, v115 offset:1056
	ds_write_b16_d16_hi v114, v115 offset:1584
	v_mfma_f32_32x32x16_bf16 v[66:81], v[182:185], v[130:133], v[66:81]
	v_cvt_pk_bf16_f32 v115, v118, v119
	ds_write_b16 v114, v115 offset:4224
	ds_write_b16_d16_hi v114, v115 offset:4752
	v_cvt_pk_bf16_f32 v115, v120, v121
	ds_write_b16 v114, v115 offset:5280
	ds_write_b16_d16_hi v114, v115 offset:5808
	v_cvt_pk_bf16_f32 v115, v122, v123
	ds_write_b16 v114, v115 offset:8448
	ds_write_b16_d16_hi v114, v115 offset:8976
	v_mfma_f32_32x32x16_bf16 v[82:97], v[190:193], v[234:237], v[82:97]
	v_cvt_pk_bf16_f32 v115, v124, v125
	ds_write_b16 v114, v115 offset:9504
	ds_write_b16_d16_hi v114, v115 offset:10032
	v_cvt_pk_bf16_f32 v115, v126, v127
	ds_write_b16 v114, v115 offset:12672
	ds_write_b16_d16_hi v114, v115 offset:13200
	v_cvt_pk_bf16_f32 v115, v128, v129
	ds_write_b16 v114, v115 offset:13728
	ds_write_b16_d16_hi v114, v115 offset:14256
	v_mfma_f32_32x32x16_bf16 v[98:113], v[202:205], v[206:209], v[98:113]
	v_mfma_f32_32x32x16_bf16 v[50:65], v[138:141], v[178:181], v[50:65]
	s_nop 10
	v_cvt_pk_bf16_f32 v98, v98, v99
	ds_write_b16 v114, v98 offset:64
	ds_write_b16_d16_hi v114, v98 offset:592
	v_cvt_pk_bf16_f32 v98, v100, v101
	ds_write_b16 v114, v98 offset:1120
	ds_write_b16_d16_hi v114, v98 offset:1648
	v_cvt_pk_bf16_f32 v98, v102, v103
	ds_write_b16 v114, v98 offset:4288
	ds_write_b16_d16_hi v114, v98 offset:4816
	v_cvt_pk_bf16_f32 v98, v104, v105
	v_mfma_f32_32x32x16_bf16 v[66:81], v[190:193], v[230:233], v[66:81]
	ds_write_b16 v114, v98 offset:5344
	ds_write_b16_d16_hi v114, v98 offset:5872
	v_cvt_pk_bf16_f32 v98, v106, v107
	ds_write_b16 v114, v98 offset:8512
	ds_write_b16_d16_hi v114, v98 offset:9040
	v_cvt_pk_bf16_f32 v98, v108, v109
	ds_write_b16 v114, v98 offset:9568
	ds_write_b16_d16_hi v114, v98 offset:10096
	v_cvt_pk_bf16_f32 v98, v110, v111
	v_mfma_f32_32x32x16_bf16 v[82:97], v[202:205], v[226:229], v[82:97]
	ds_write_b16 v114, v98 offset:12736
	ds_write_b16_d16_hi v114, v98 offset:13264
	v_cvt_pk_bf16_f32 v98, v112, v113
	ds_write_b16 v114, v98 offset:13792
	ds_write_b16_d16_hi v114, v98 offset:14320
	s_nop 6
	v_cvt_pk_bf16_f32 v82, v82, v83
	v_mfma_f32_32x32x16_bf16 v[18:33], v[134:137], v[186:189], v[18:33]
	ds_write_b16 v114, v82 offset:128
	ds_write_b16_d16_hi v114, v82 offset:656
	v_cvt_pk_bf16_f32 v82, v84, v85
	ds_write_b16 v114, v82 offset:1184
	ds_write_b16_d16_hi v114, v82 offset:1712
	v_cvt_pk_bf16_f32 v82, v86, v87
	ds_write_b16 v114, v82 offset:4352
	ds_write_b16_d16_hi v114, v82 offset:4880
	v_cvt_pk_bf16_f32 v82, v88, v89
	v_mfma_f32_32x32x16_bf16 v[34:49], v[138:141], v[174:177], v[34:49]
	ds_write_b16 v114, v82 offset:5408
	ds_write_b16_d16_hi v114, v82 offset:5936
	v_cvt_pk_bf16_f32 v82, v90, v91
	ds_write_b16 v114, v82 offset:8576
	ds_write_b16_d16_hi v114, v82 offset:9104
	v_cvt_pk_bf16_f32 v82, v92, v93
	ds_write_b16 v114, v82 offset:9632
	ds_write_b16_d16_hi v114, v82 offset:10160
	v_cvt_pk_bf16_f32 v82, v94, v95
	ds_write_b16 v114, v82 offset:12800
	ds_write_b16_d16_hi v114, v82 offset:13328
	v_mfma_f32_32x32x16_bf16 v[50:65], v[218:221], v[194:197], v[50:65]
	v_cvt_pk_bf16_f32 v82, v96, v97
	ds_write_b16 v114, v82 offset:13856
; DI unsigned pk2(float a, float b) { fl2_t f = {a, b}; bf2_t r = __builtin_convertvector(f, bf2_t); return __builtin_bit_cast(unsigned, r); }
; template <typename FA, typename FB, typename FE>
; DI void gemm_tile(char* lds, int K, int astride, int bstride, FA arow, FB brow, FE epi) {
;     ...
; #pragma unroll
;   for (int mt = 0; mt < 2; ++mt)
; #pragma unroll
;     for (int nt = 0; nt < 4; ++nt)
; #pragma unroll
;       for (int i = 0; i < 16; i += 2) {
;         const int row = wm * 64 + mt * 32 + (i & 3) + 8 * (i >> 2) + 4 * h8;
;         const unsigned pr = pk2(acc[mt][nt][i], acc[mt][nt][i + 1]);
;         Cs[row * CSS + wn * 128 + nt * 32 + r] = (bfr)(pr & 0xffffu);
;         Cs[(row + 1) * CSS + wn * 128 + nt * 32 + r] = (bfr)(pr >> 16);
;       }
;   __syncthreads();
; DI void phase_moe(const Params& p, char* lds, int mode) {
;     ...
;         const int row = tid & 127, hf = tid >> 7, grow = half * 128 + row;
;         if (r0 + grow < n) {
	ds_write_b16_d16_hi v114, v82 offset:14384
	v_mfma_f32_32x32x16_bf16 v[66:81], v[202:205], v[222:225], v[66:81]
	v_mfma_f32_32x32x16_bf16 v[2:17], v[134:137], v[142:145], v[2:17]
	s_nop 10
	v_cvt_pk_bf16_f32 v66, v66, v67
	ds_write_b16 v114, v66 offset:192
	ds_write_b16_d16_hi v114, v66 offset:720
	v_cvt_pk_bf16_f32 v66, v68, v69
	ds_write_b16 v114, v66 offset:1248
	ds_write_b16_d16_hi v114, v66 offset:1776
	v_cvt_pk_bf16_f32 v66, v70, v71
	ds_write_b16 v114, v66 offset:4416
	ds_write_b16_d16_hi v114, v66 offset:4944
	v_mfma_f32_32x32x16_bf16 v[18:33], v[138:141], v[146:149], v[18:33]
	v_cvt_pk_bf16_f32 v66, v72, v73
	ds_write_b16 v114, v66 offset:5472
	ds_write_b16_d16_hi v114, v66 offset:6000
	v_cvt_pk_bf16_f32 v66, v74, v75
	ds_write_b16 v114, v66 offset:8640
	ds_write_b16_d16_hi v114, v66 offset:9168
	v_cvt_pk_bf16_f32 v66, v76, v77
	ds_write_b16 v114, v66 offset:9696
	ds_write_b16_d16_hi v114, v66 offset:10224
	v_cvt_pk_bf16_f32 v66, v78, v79
	v_mfma_f32_32x32x16_bf16 v[34:49], v[218:221], v[214:217], v[34:49]
	ds_write_b16 v114, v66 offset:12864
	ds_write_b16_d16_hi v114, v66 offset:13392
	v_cvt_pk_bf16_f32 v66, v80, v81
	ds_write_b16 v114, v66 offset:13920
	ds_write_b16_d16_hi v114, v66 offset:14448
	v_mfma_f32_32x32x16_bf16 v[50:65], v[198:201], v[210:213], v[50:65]
	v_mfma_f32_32x32x16_bf16 v[2:17], v[138:141], v[130:133], v[2:17]
	s_nop 10
	v_cvt_pk_bf16_f32 v50, v50, v51
	ds_write_b16 v114, v50 offset:16896
	ds_write_b16_d16_hi v114, v50 offset:17424
	v_cvt_pk_bf16_f32 v50, v52, v53
	ds_write_b16 v114, v50 offset:17952
	ds_write_b16_d16_hi v114, v50 offset:18480
	v_cvt_pk_bf16_f32 v50, v54, v55
	ds_write_b16 v114, v50 offset:21120
	ds_write_b16_d16_hi v114, v50 offset:21648
	v_mfma_f32_32x32x16_bf16 v[18:33], v[218:221], v[234:237], v[18:33]
	v_cvt_pk_bf16_f32 v50, v56, v57
	ds_write_b16 v114, v50 offset:22176
	ds_write_b16_d16_hi v114, v50 offset:22704
	v_cvt_pk_bf16_f32 v50, v58, v59
	ds_write_b16 v114, v50 offset:25344
	ds_write_b16_d16_hi v114, v50 offset:25872
	v_cvt_pk_bf16_f32 v50, v60, v61
	ds_write_b16 v114, v50 offset:26400
	ds_write_b16_d16_hi v114, v50 offset:26928
	v_cvt_pk_bf16_f32 v50, v62, v63
	v_mfma_f32_32x32x16_bf16 v[34:49], v[198:201], v[206:209], v[34:49]
	ds_write_b16 v114, v50 offset:29568
	ds_write_b16_d16_hi v114, v50 offset:30096
	v_cvt_pk_bf16_f32 v50, v64, v65
	ds_write_b16 v114, v50 offset:30624
	ds_write_b16_d16_hi v114, v50 offset:31152
	s_nop 6
	v_cvt_pk_bf16_f32 v34, v34, v35
	v_mfma_f32_32x32x16_bf16 v[2:17], v[218:221], v[230:233], v[2:17]
	ds_write_b16 v114, v34 offset:16960
	ds_write_b16_d16_hi v114, v34 offset:17488
	v_cvt_pk_bf16_f32 v34, v36, v37
	ds_write_b16 v114, v34 offset:18016
	ds_write_b16_d16_hi v114, v34 offset:18544
	v_cvt_pk_bf16_f32 v34, v38, v39
	ds_write_b16 v114, v34 offset:21184
	ds_write_b16_d16_hi v114, v34 offset:21712
	v_cvt_pk_bf16_f32 v34, v40, v41
	ds_write_b16 v114, v34 offset:22240
	ds_write_b16_d16_hi v114, v34 offset:22768
	v_mfma_f32_32x32x16_bf16 v[18:33], v[198:201], v[226:229], v[18:33]
	v_cvt_pk_bf16_f32 v34, v42, v43
	ds_write_b16 v114, v34 offset:25408
	ds_write_b16_d16_hi v114, v34 offset:25936
	v_cvt_pk_bf16_f32 v34, v44, v45
	ds_write_b16 v114, v34 offset:26464
	ds_write_b16_d16_hi v114, v34 offset:26992
	v_cvt_pk_bf16_f32 v34, v46, v47
	ds_write_b16 v114, v34 offset:29632
	ds_write_b16_d16_hi v114, v34 offset:30160
	v_mfma_f32_32x32x16_bf16 v[2:17], v[198:201], v[222:225], v[2:17]
	v_cvt_pk_bf16_f32 v34, v48, v49
	s_nop 0
	v_cvt_pk_bf16_f32 v18, v18, v19
	ds_write_b16 v114, v34 offset:30688
	ds_write_b16_d16_hi v114, v34 offset:31216
	ds_write_b16 v114, v18 offset:17024
	ds_write_b16_d16_hi v114, v18 offset:17552
	v_cvt_pk_bf16_f32 v18, v20, v21
	ds_write_b16 v114, v18 offset:18080
	ds_write_b16_d16_hi v114, v18 offset:18608
	v_cvt_pk_bf16_f32 v18, v22, v23
	ds_write_b16 v114, v18 offset:21248
	ds_write_b16_d16_hi v114, v18 offset:21776
	v_cvt_pk_bf16_f32 v18, v24, v25
	ds_write_b16 v114, v18 offset:22304
	ds_write_b16_d16_hi v114, v18 offset:22832
	v_cvt_pk_bf16_f32 v18, v26, v27
	ds_write_b16 v114, v18 offset:25472
	ds_write_b16_d16_hi v114, v18 offset:26000
	v_cvt_pk_bf16_f32 v18, v28, v29
	ds_write_b16 v114, v18 offset:26528
	ds_write_b16_d16_hi v114, v18 offset:27056
	v_cvt_pk_bf16_f32 v18, v30, v31
	ds_write_b16 v114, v18 offset:29696
	ds_write_b16_d16_hi v114, v18 offset:30224
	v_cvt_pk_bf16_f32 v18, v32, v33
	v_cvt_pk_bf16_f32 v2, v2, v3
	ds_write_b16 v114, v18 offset:30752
	ds_write_b16_d16_hi v114, v18 offset:31280
	ds_write_b16 v114, v2 offset:17088
	ds_write_b16_d16_hi v114, v2 offset:17616
	v_cvt_pk_bf16_f32 v2, v4, v5
	ds_write_b16 v114, v2 offset:18144
	ds_write_b16_d16_hi v114, v2 offset:18672
	v_cvt_pk_bf16_f32 v2, v6, v7
	ds_write_b16 v114, v2 offset:21312
	ds_write_b16_d16_hi v114, v2 offset:21840
	v_cvt_pk_bf16_f32 v2, v8, v9
	ds_write_b16 v114, v2 offset:22368
	ds_write_b16_d16_hi v114, v2 offset:22896
	v_cvt_pk_bf16_f32 v2, v10, v11
	ds_write_b16 v114, v2 offset:25536
	ds_write_b16_d16_hi v114, v2 offset:26064
	v_cvt_pk_bf16_f32 v2, v12, v13
	ds_write_b16 v114, v2 offset:26592
	ds_write_b16_d16_hi v114, v2 offset:27120
	v_cvt_pk_bf16_f32 v2, v14, v15
	ds_write_b16 v114, v2 offset:29760
	ds_write_b16_d16_hi v114, v2 offset:30288
	v_cvt_pk_bf16_f32 v2, v16, v17
	ds_write_b16 v114, v2 offset:30816
	ds_write_b16_d16_hi v114, v2 offset:31344
	v_add_u32_e32 v2, v162, v168
	s_waitcnt vmcnt(0)
	v_cmp_lt_i32_e32 vcc, v2, v167
	s_waitcnt lgkmcnt(0)
	s_barrier
	s_and_saveexec_b64 s[24:25], vcc
	s_cbranch_execz .LBB0_289
; DI unsigned pk2(float a, float b) { fl2_t f = {a, b}; bf2_t r = __builtin_convertvector(f, bf2_t); return __builtin_bit_cast(unsigned, r); }
; DI void phase_moe(const Params& p, char* lds, int mode) {
;     ...
;         const int row = tid & 127, hf = tid >> 7, grow = half * 128 + row;
;         if (r0 + grow < n) {
;           bfr* dst = act + ((size_t)(nt * 2 + hf) * (2 * T) + (lb[li] + r0 + grow)) * 32;
; #pragma unroll
;           for (int q = 0; q < 4; ++q) {
;             float z[8];
; #pragma unroll
;             for (int u = 0; u < 2; ++u) {
;               float4 g = cs4(Cs, row, hf * 32 + q * 8 + u * 4);
;               float4 up = cs4(Cs, row, 64 + hf * 32 + q * 8 + u * 4);
;               z[u * 4 + 0] = g.x / (1.f + __expf(-g.x)) * up.x; z[u * 4 + 1] = g.y / (1.f + __expf(-g.y)) * up.y;
;               z[u * 4 + 2] = g.z / (1.f + __expf(-g.z)) * up.z; z[u * 4 + 3] = g.w / (1.f + __expf(-g.w)) * up.w;
;             }
;             u32x4 o; o[0] = pk2(z[0], z[1]); o[1] = pk2(z[2], z[3]); o[2] = pk2(z[4], z[5]); o[3] = pk2(z[6], z[7]);
;             *(u32x4*)(dst + q * 8) = o;
;           }
;         }
	s_add_i32 s16, s39, 0x25e00
	v_mov_b32_e32 v3, s16
	ds_read_b32 v3, v3
	ds_read_b128 v[18:21], v164
	ds_read_b128 v[10:13], v164 offset:16
	v_lshl_or_b32 v30, s37, 2, v163
	s_waitcnt lgkmcnt(1)
	v_lshlrev_b32_e32 v31, 16, v18
	v_add_u32_e32 v26, v3, v2
	v_ashrrev_i32_e32 v27, 31, v26
	v_mad_i64_i32 v[2:3], s[26:27], v30, s36, v[26:27]
	v_lshlrev_b64 v[2:3], 6, v[2:3]
	v_lshl_add_u64 v[28:29], s[10:11], 0, v[2:3]
	v_and_b32_e32 v18, 0xffff0000, v18
	v_mul_f32_e32 v2, 0xbfb8aa3b, v31
	v_exp_f32_e32 v14, v2
	v_mul_f32_e32 v2, 0xbfb8aa3b, v18
	v_exp_f32_e32 v15, v2
	ds_read_b128 v[6:9], v164 offset:32
	ds_read_b128 v[2:5], v164 offset:48
	ds_read_b128 v[22:25], v164 offset:128
	v_pk_add_f32 v[32:33], v[14:15], 1.0 op_sel_hi:[1,0]
	s_nop 0
	s_waitcnt lgkmcnt(0)
	v_lshlrev_b32_e32 v34, 16, v22
	v_and_b32_e32 v35, 0xffff0000, v22
	ds_read_b128 v[14:17], v164 offset:144
	v_rcp_f32_e32 v22, v33
	v_and_b32_e32 v38, 0xffff0000, v19
	v_mul_f32_e32 v33, v18, v22
	v_lshlrev_b32_e32 v37, 16, v19
	v_mul_f32_e32 v18, 0xbfb8aa3b, v37
	v_mul_f32_e32 v19, 0xbfb8aa3b, v38
	v_exp_f32_e32 v18, v18
	v_exp_f32_e32 v19, v19
	v_rcp_f32_e32 v22, v32
	s_nop 0
	v_mul_f32_e32 v32, v31, v22
	v_pk_mul_f32 v[32:33], v[32:33], v[34:35]
	v_pk_add_f32 v[18:19], v[18:19], 1.0 op_sel_hi:[1,0]
	v_lshlrev_b32_e32 v22, 16, v23
	v_and_b32_e32 v23, 0xffff0000, v23
	v_rcp_f32_e32 v31, v19
	s_nop 0
	v_mul_f32_e32 v19, v38, v31
	v_lshlrev_b32_e32 v38, 16, v20
	v_and_b32_e32 v20, 0xffff0000, v20
	v_mul_f32_e32 v34, 0xbfb8aa3b, v38
	v_mul_f32_e32 v35, 0xbfb8aa3b, v20
	v_exp_f32_e32 v34, v34
	v_exp_f32_e32 v35, v35
	v_rcp_f32_e32 v31, v18
	s_nop 0
	v_mul_f32_e32 v18, v37, v31
	v_pk_mul_f32 v[22:23], v[18:19], v[22:23]
	v_pk_add_f32 v[34:35], v[34:35], 1.0 op_sel_hi:[1,0]
	v_lshlrev_b32_e32 v18, 16, v24
	v_and_b32_e32 v19, 0xffff0000, v24
	v_rcp_f32_e32 v24, v35
	v_and_b32_e32 v37, 0xffff0000, v21
	v_mul_f32_e32 v35, v20, v24
	v_lshlrev_b32_e32 v36, 16, v21
	v_mul_f32_e32 v20, 0xbfb8aa3b, v36
	v_mul_f32_e32 v21, 0xbfb8aa3b, v37
	v_exp_f32_e32 v20, v20
	v_exp_f32_e32 v21, v21
	v_rcp_f32_e32 v24, v34
	s_nop 0
	v_mul_f32_e32 v34, v38, v24
	v_pk_mul_f32 v[34:35], v[34:35], v[18:19]
	v_pk_add_f32 v[20:21], v[20:21], 1.0 op_sel_hi:[1,0]
	v_lshlrev_b32_e32 v18, 16, v25
	v_and_b32_e32 v19, 0xffff0000, v25
	v_rcp_f32_e32 v24, v21
	s_nop 0
	v_mul_f32_e32 v21, v37, v24
	v_rcp_f32_e32 v24, v20
	v_lshlrev_b32_e32 v31, 16, v10
	v_mul_f32_e32 v20, v36, v24
	v_pk_mul_f32 v[24:25], v[20:21], v[18:19]
	v_and_b32_e32 v10, 0xffff0000, v10
	v_mul_f32_e32 v19, 0xbfb8aa3b, v31
	v_cvt_pk_bf16_f32 v18, v32, v33
	v_exp_f32_e32 v32, v19
	v_mul_f32_e32 v19, 0xbfb8aa3b, v10
	v_exp_f32_e32 v33, v19
	v_cvt_pk_bf16_f32 v19, v22, v23
	v_cvt_pk_bf16_f32 v21, v24, v25
	v_cvt_pk_bf16_f32 v20, v34, v35
	v_pk_add_f32 v[22:23], v[32:33], 1.0 op_sel_hi:[1,0]
	global_store_dwordx4 v[28:29], v[18:21], off
	s_nop 1
	s_waitcnt lgkmcnt(0)
	v_lshlrev_b32_e32 v18, 16, v14
	v_and_b32_e32 v19, 0xffff0000, v14
	v_rcp_f32_e32 v14, v23
	s_nop 0
	v_mul_f32_e32 v21, v10, v14
	v_lshlrev_b32_e32 v23, 16, v11
	v_and_b32_e32 v24, 0xffff0000, v11
	v_mul_f32_e32 v10, 0xbfb8aa3b, v23
	v_mul_f32_e32 v11, 0xbfb8aa3b, v24
	v_exp_f32_e32 v10, v10
	v_exp_f32_e32 v11, v11
	v_rcp_f32_e32 v14, v22
	s_nop 0
	v_mul_f32_e32 v20, v31, v14
	v_pk_mul_f32 v[18:19], v[20:21], v[18:19]
	v_pk_add_f32 v[10:11], v[10:11], 1.0 op_sel_hi:[1,0]
	v_lshlrev_b32_e32 v14, 16, v15
	v_and_b32_e32 v15, 0xffff0000, v15
	v_rcp_f32_e32 v20, v11
	v_lshlrev_b32_e32 v25, 16, v12
	v_mul_f32_e32 v11, v24, v20
	v_and_b32_e32 v12, 0xffff0000, v12
	v_mul_f32_e32 v20, 0xbfb8aa3b, v25
	v_mul_f32_e32 v21, 0xbfb8aa3b, v12
	v_exp_f32_e32 v20, v20
	v_exp_f32_e32 v21, v21
	v_rcp_f32_e32 v22, v10
	s_nop 0
	v_mul_f32_e32 v10, v23, v22
	v_pk_mul_f32 v[14:15], v[10:11], v[14:15]
	v_pk_add_f32 v[20:21], v[20:21], 1.0 op_sel_hi:[1,0]
	v_lshlrev_b32_e32 v10, 16, v16
	v_and_b32_e32 v11, 0xffff0000, v16
	v_rcp_f32_e32 v16, v21
	v_and_b32_e32 v24, 0xffff0000, v13
	v_mul_f32_e32 v21, v12, v16
	v_lshlrev_b32_e32 v23, 16, v13
	v_mul_f32_e32 v12, 0xbfb8aa3b, v23
	v_mul_f32_e32 v13, 0xbfb8aa3b, v24
	v_exp_f32_e32 v12, v12
	v_exp_f32_e32 v13, v13
	v_rcp_f32_e32 v16, v20
	s_nop 0
	v_mul_f32_e32 v20, v25, v16
	v_pk_mul_f32 v[20:21], v[20:21], v[10:11]
	v_pk_add_f32 v[12:13], v[12:13], 1.0 op_sel_hi:[1,0]
	v_lshlrev_b32_e32 v10, 16, v17
	v_and_b32_e32 v11, 0xffff0000, v17
	v_rcp_f32_e32 v16, v13
	s_nop 0
	v_mul_f32_e32 v13, v24, v16
	v_rcp_f32_e32 v16, v12
	v_lshlrev_b32_e32 v22, 16, v6
	v_mul_f32_e32 v12, v23, v16
	v_pk_mul_f32 v[16:17], v[12:13], v[10:11]
	v_and_b32_e32 v6, 0xffff0000, v6
	v_mul_f32_e32 v13, 0xbfb8aa3b, v22
	v_cvt_pk_bf16_f32 v10, v18, v19
	v_exp_f32_e32 v18, v13
	v_mul_f32_e32 v13, 0xbfb8aa3b, v6
	v_exp_f32_e32 v19, v13
	v_cvt_pk_bf16_f32 v11, v14, v15
	v_cvt_pk_bf16_f32 v13, v16, v17
	ds_read_b128 v[14:17], v164 offset:160
	v_pk_add_f32 v[18:19], v[18:19], 1.0 op_sel_hi:[1,0]
	v_cvt_pk_bf16_f32 v12, v20, v21
	s_waitcnt lgkmcnt(0)
; DI unsigned pk2(float a, float b) { fl2_t f = {a, b}; bf2_t r = __builtin_convertvector(f, bf2_t); return __builtin_bit_cast(unsigned, r); }
; DI void phase_moe(const Params& p, char* lds, int mode) {
;     ...
; #pragma unroll
;           for (int q = 0; q < 4; ++q) {
;             float z[8];
; #pragma unroll
;             for (int u = 0; u < 2; ++u) {
;               float4 g = cs4(Cs, row, hf * 32 + q * 8 + u * 4);
;               float4 up = cs4(Cs, row, 64 + hf * 32 + q * 8 + u * 4);
;               z[u * 4 + 0] = g.x / (1.f + __expf(-g.x)) * up.x; z[u * 4 + 1] = g.y / (1.f + __expf(-g.y)) * up.y;
;               z[u * 4 + 2] = g.z / (1.f + __expf(-g.z)) * up.z; z[u * 4 + 3] = g.w / (1.f + __expf(-g.w)) * up.w;
;             }
;             u32x4 o; o[0] = pk2(z[0], z[1]); o[1] = pk2(z[2], z[3]); o[2] = pk2(z[4], z[5]); o[3] = pk2(z[6], z[7]);
;             *(u32x4*)(dst + q * 8) = o;
;           }
;         }
	v_lshlrev_b32_e32 v20, 16, v14
	v_and_b32_e32 v21, 0xffff0000, v14
	global_store_dwordx4 v[28:29], v[10:13], off offset:16
	v_rcp_f32_e32 v14, v19
	v_and_b32_e32 v25, 0xffff0000, v7
	v_mul_f32_e32 v19, v6, v14
	v_lshlrev_b32_e32 v24, 16, v7
	v_mul_f32_e32 v6, 0xbfb8aa3b, v24
	v_mul_f32_e32 v7, 0xbfb8aa3b, v25
	v_exp_f32_e32 v6, v6
	v_exp_f32_e32 v7, v7
	v_rcp_f32_e32 v14, v18
	s_nop 0
	v_mul_f32_e32 v18, v22, v14
	v_pk_mul_f32 v[18:19], v[18:19], v[20:21]
	v_pk_add_f32 v[6:7], v[6:7], 1.0 op_sel_hi:[1,0]
	v_lshlrev_b32_e32 v14, 16, v15
	v_and_b32_e32 v15, 0xffff0000, v15
	ds_read_b128 v[10:13], v164 offset:176
	v_rcp_f32_e32 v20, v7
	s_nop 0
	v_mul_f32_e32 v7, v25, v20
	v_lshlrev_b32_e32 v25, 16, v8
	v_and_b32_e32 v8, 0xffff0000, v8
	v_mul_f32_e32 v20, 0xbfb8aa3b, v25
	v_mul_f32_e32 v21, 0xbfb8aa3b, v8
	v_exp_f32_e32 v20, v20
	v_exp_f32_e32 v21, v21
	v_rcp_f32_e32 v22, v6
	s_nop 0
	v_mul_f32_e32 v6, v24, v22
	v_pk_mul_f32 v[14:15], v[6:7], v[14:15]
	v_pk_add_f32 v[20:21], v[20:21], 1.0 op_sel_hi:[1,0]
	v_lshlrev_b32_e32 v6, 16, v16
	v_and_b32_e32 v7, 0xffff0000, v16
	v_rcp_f32_e32 v16, v21
	v_and_b32_e32 v24, 0xffff0000, v9
	v_mul_f32_e32 v21, v8, v16
	v_lshlrev_b32_e32 v23, 16, v9
	v_mul_f32_e32 v8, 0xbfb8aa3b, v23
	v_mul_f32_e32 v9, 0xbfb8aa3b, v24
	v_exp_f32_e32 v8, v8
	v_exp_f32_e32 v9, v9
	v_rcp_f32_e32 v16, v20
	s_nop 0
	v_mul_f32_e32 v20, v25, v16
	v_pk_mul_f32 v[20:21], v[20:21], v[6:7]
	v_pk_add_f32 v[8:9], v[8:9], 1.0 op_sel_hi:[1,0]
	v_lshlrev_b32_e32 v6, 16, v17
	v_and_b32_e32 v7, 0xffff0000, v17
	v_rcp_f32_e32 v16, v9
	s_nop 0
	v_mul_f32_e32 v9, v24, v16
	v_rcp_f32_e32 v16, v8
	v_lshlrev_b32_e32 v22, 16, v2
	v_mul_f32_e32 v8, v23, v16
	v_pk_mul_f32 v[16:17], v[8:9], v[6:7]
	v_and_b32_e32 v2, 0xffff0000, v2
	v_mul_f32_e32 v7, 0xbfb8aa3b, v22
	v_cvt_pk_bf16_f32 v6, v18, v19
	v_exp_f32_e32 v18, v7
	v_mul_f32_e32 v7, 0xbfb8aa3b, v2
	v_exp_f32_e32 v19, v7
	v_cvt_pk_bf16_f32 v7, v14, v15
	v_cvt_pk_bf16_f32 v9, v16, v17
	v_cvt_pk_bf16_f32 v8, v20, v21
	v_pk_add_f32 v[14:15], v[18:19], 1.0 op_sel_hi:[1,0]
	global_store_dwordx4 v[28:29], v[6:9], off offset:32
	s_nop 1
	s_waitcnt lgkmcnt(0)
	v_lshlrev_b32_e32 v6, 16, v10
	v_and_b32_e32 v7, 0xffff0000, v10
	v_rcp_f32_e32 v8, v15
	v_and_b32_e32 v17, 0xffff0000, v3
	v_mul_f32_e32 v9, v2, v8
	v_lshlrev_b32_e32 v15, 16, v3
	v_mul_f32_e32 v2, 0xbfb8aa3b, v15
	v_mul_f32_e32 v3, 0xbfb8aa3b, v17
	v_exp_f32_e32 v2, v2
	v_exp_f32_e32 v3, v3
	v_rcp_f32_e32 v8, v14
	s_nop 0
	v_mul_f32_e32 v8, v22, v8
	v_pk_mul_f32 v[6:7], v[8:9], v[6:7]
	v_pk_add_f32 v[2:3], v[2:3], 1.0 op_sel_hi:[1,0]
	v_lshlrev_b32_e32 v8, 16, v11
	v_and_b32_e32 v9, 0xffff0000, v11
	v_rcp_f32_e32 v10, v3
	s_nop 0
	v_mul_f32_e32 v3, v17, v10
	v_lshlrev_b32_e32 v17, 16, v4
	v_and_b32_e32 v4, 0xffff0000, v4
	v_mul_f32_e32 v10, 0xbfb8aa3b, v17
	v_mul_f32_e32 v11, 0xbfb8aa3b, v4
	v_exp_f32_e32 v10, v10
	v_exp_f32_e32 v11, v11
	v_rcp_f32_e32 v14, v2
	s_nop 0
	v_mul_f32_e32 v2, v15, v14
	v_pk_mul_f32 v[8:9], v[2:3], v[8:9]
	v_pk_add_f32 v[10:11], v[10:11], 1.0 op_sel_hi:[1,0]
	v_lshlrev_b32_e32 v2, 16, v12
	v_and_b32_e32 v3, 0xffff0000, v12
	v_rcp_f32_e32 v12, v11
	v_and_b32_e32 v16, 0xffff0000, v5
	v_mul_f32_e32 v11, v4, v12
	v_lshlrev_b32_e32 v15, 16, v5
	v_mul_f32_e32 v4, 0xbfb8aa3b, v15
	v_mul_f32_e32 v5, 0xbfb8aa3b, v16
	v_exp_f32_e32 v4, v4
	v_exp_f32_e32 v5, v5
	v_rcp_f32_e32 v12, v10
	s_nop 0
	v_mul_f32_e32 v10, v17, v12
	v_pk_mul_f32 v[10:11], v[10:11], v[2:3]
	v_pk_add_f32 v[4:5], v[4:5], 1.0 op_sel_hi:[1,0]
	v_lshlrev_b32_e32 v2, 16, v13
	v_and_b32_e32 v3, 0xffff0000, v13
	v_rcp_f32_e32 v12, v5
	s_nop 0
	v_mul_f32_e32 v5, v16, v12
	v_rcp_f32_e32 v12, v4
	s_nop 0
	v_mul_f32_e32 v4, v15, v12
	v_pk_mul_f32 v[12:13], v[4:5], v[2:3]
	v_cvt_pk_bf16_f32 v4, v10, v11
	v_cvt_pk_bf16_f32 v5, v12, v13
	ds_read_b128 v[10:13], v164 offset:256
	v_cvt_pk_bf16_f32 v2, v6, v7
	v_cvt_pk_bf16_f32 v3, v8, v9
	global_store_dwordx4 v[28:29], v[2:5], off offset:48
	ds_read_b128 v[16:19], v164 offset:384
	s_waitcnt lgkmcnt(1)
	v_lshlrev_b32_e32 v24, 16, v10
	v_and_b32_e32 v10, 0xffff0000, v10
	v_mul_f32_e32 v4, 0xbfb8aa3b, v24
	v_mul_f32_e32 v5, 0xbfb8aa3b, v10
	v_exp_f32_e32 v4, v4
	v_exp_f32_e32 v5, v5
	v_or_b32_e32 v2, 2, v30
	v_mad_i64_i32 v[2:3], s[26:27], v2, s36, v[26:27]
	v_pk_add_f32 v[20:21], v[4:5], 1.0 op_sel_hi:[1,0]
	s_waitcnt lgkmcnt(0)
	v_lshlrev_b32_e32 v22, 16, v16
	v_and_b32_e32 v23, 0xffff0000, v16
	ds_read_b128 v[6:9], v164 offset:272
	v_lshlrev_b64 v[2:3], 6, v[2:3]
	v_rcp_f32_e32 v16, v21
	v_and_b32_e32 v27, 0xffff0000, v11
	v_mul_f32_e32 v21, v10, v16
	v_lshlrev_b32_e32 v26, 16, v11
	v_mul_f32_e32 v10, 0xbfb8aa3b, v26
	v_mul_f32_e32 v11, 0xbfb8aa3b, v27
	v_exp_f32_e32 v10, v10
	v_exp_f32_e32 v11, v11
	v_rcp_f32_e32 v16, v20
	s_nop 0
	v_mul_f32_e32 v20, v24, v16
	v_pk_mul_f32 v[20:21], v[20:21], v[22:23]
	v_pk_add_f32 v[10:11], v[10:11], 1.0 op_sel_hi:[1,0]
	v_lshlrev_b32_e32 v16, 16, v17
	v_and_b32_e32 v17, 0xffff0000, v17
	v_lshl_add_u64 v[14:15], s[10:11], 0, v[2:3]
	ds_read_b128 v[2:5], v164 offset:400
	v_rcp_f32_e32 v22, v11
	s_nop 0
	v_mul_f32_e32 v11, v27, v22
	v_lshlrev_b32_e32 v27, 16, v12
	v_and_b32_e32 v12, 0xffff0000, v12
	v_mul_f32_e32 v22, 0xbfb8aa3b, v27
	v_mul_f32_e32 v23, 0xbfb8aa3b, v12
	v_exp_f32_e32 v22, v22
	v_exp_f32_e32 v23, v23
	v_rcp_f32_e32 v24, v10
	s_nop 0
	v_mul_f32_e32 v10, v26, v24
	v_pk_mul_f32 v[16:17], v[10:11], v[16:17]
	v_pk_add_f32 v[22:23], v[22:23], 1.0 op_sel_hi:[1,0]
	v_lshlrev_b32_e32 v10, 16, v18
	v_and_b32_e32 v11, 0xffff0000, v18
	v_rcp_f32_e32 v18, v23
	v_and_b32_e32 v26, 0xffff0000, v13
	v_mul_f32_e32 v23, v12, v18
	v_lshlrev_b32_e32 v25, 16, v13
	v_mul_f32_e32 v12, 0xbfb8aa3b, v25
	v_mul_f32_e32 v13, 0xbfb8aa3b, v26
	v_exp_f32_e32 v12, v12
	v_exp_f32_e32 v13, v13
	v_rcp_f32_e32 v18, v22
	s_nop 0
	v_mul_f32_e32 v22, v27, v18
	v_pk_mul_f32 v[22:23], v[22:23], v[10:11]
	v_pk_add_f32 v[12:13], v[12:13], 1.0 op_sel_hi:[1,0]
	v_lshlrev_b32_e32 v10, 16, v19
	v_and_b32_e32 v11, 0xffff0000, v19
	v_rcp_f32_e32 v18, v13
	s_nop 0
	v_mul_f32_e32 v13, v26, v18
	v_rcp_f32_e32 v18, v12
	s_nop 0
	v_mul_f32_e32 v12, v25, v18
	s_waitcnt lgkmcnt(1)
; DI unsigned pk2(float a, float b) { fl2_t f = {a, b}; bf2_t r = __builtin_convertvector(f, bf2_t); return __builtin_bit_cast(unsigned, r); }
; DI void phase_moe(const Params& p, char* lds, int mode) {
;     ...
; #pragma unroll
;           for (int q = 0; q < 4; ++q) {
;             float z[8];
; #pragma unroll
;             for (int u = 0; u < 2; ++u) {
;               float4 g = cs4(Cs, row, hf * 32 + q * 8 + u * 4);
;               float4 up = cs4(Cs, row, 64 + hf * 32 + q * 8 + u * 4);
;               z[u * 4 + 0] = g.x / (1.f + __expf(-g.x)) * up.x; z[u * 4 + 1] = g.y / (1.f + __expf(-g.y)) * up.y;
;               z[u * 4 + 2] = g.z / (1.f + __expf(-g.z)) * up.z; z[u * 4 + 3] = g.w / (1.f + __expf(-g.w)) * up.w;
;             }
;             u32x4 o; o[0] = pk2(z[0], z[1]); o[1] = pk2(z[2], z[3]); o[2] = pk2(z[4], z[5]); o[3] = pk2(z[6], z[7]);
;             *(u32x4*)(dst + q * 8) = o;
;           }
;         }
	v_lshlrev_b32_e32 v24, 16, v6
	v_pk_mul_f32 v[18:19], v[12:13], v[10:11]
	v_and_b32_e32 v6, 0xffff0000, v6
	v_mul_f32_e32 v11, 0xbfb8aa3b, v24
	v_cvt_pk_bf16_f32 v10, v20, v21
	v_exp_f32_e32 v20, v11
	v_mul_f32_e32 v11, 0xbfb8aa3b, v6
	v_exp_f32_e32 v21, v11
	v_cvt_pk_bf16_f32 v11, v16, v17
	v_cvt_pk_bf16_f32 v13, v18, v19
	v_cvt_pk_bf16_f32 v12, v22, v23
	v_pk_add_f32 v[16:17], v[20:21], 1.0 op_sel_hi:[1,0]
	global_store_dwordx4 v[14:15], v[10:13], off
	s_nop 1
	s_waitcnt lgkmcnt(0)
	v_lshlrev_b32_e32 v10, 16, v2
	v_and_b32_e32 v11, 0xffff0000, v2
	v_rcp_f32_e32 v2, v17
	v_and_b32_e32 v19, 0xffff0000, v7
	v_mul_f32_e32 v13, v6, v2
	v_lshlrev_b32_e32 v18, 16, v7
	v_mul_f32_e32 v6, 0xbfb8aa3b, v18
	v_mul_f32_e32 v7, 0xbfb8aa3b, v19
	v_exp_f32_e32 v6, v6
	v_exp_f32_e32 v7, v7
	v_rcp_f32_e32 v2, v16
	s_nop 0
	v_mul_f32_e32 v12, v24, v2
	v_pk_mul_f32 v[16:17], v[12:13], v[10:11]
	v_pk_add_f32 v[6:7], v[6:7], 1.0 op_sel_hi:[1,0]
	v_lshlrev_b32_e32 v2, 16, v3
	v_and_b32_e32 v3, 0xffff0000, v3
	v_rcp_f32_e32 v10, v7
	v_lshlrev_b32_e32 v20, 16, v8
	v_mul_f32_e32 v7, v19, v10
	v_and_b32_e32 v8, 0xffff0000, v8
	v_mul_f32_e32 v10, 0xbfb8aa3b, v20
	v_mul_f32_e32 v11, 0xbfb8aa3b, v8
	v_exp_f32_e32 v10, v10
	v_exp_f32_e32 v11, v11
	v_rcp_f32_e32 v12, v6
	s_nop 0
	v_mul_f32_e32 v6, v18, v12
	v_pk_mul_f32 v[6:7], v[6:7], v[2:3]
	v_pk_add_f32 v[10:11], v[10:11], 1.0 op_sel_hi:[1,0]
	v_lshlrev_b32_e32 v2, 16, v4
	v_and_b32_e32 v3, 0xffff0000, v4
	v_and_b32_e32 v21, 0xffff0000, v9
	v_rcp_f32_e32 v4, v11
	v_lshlrev_b32_e32 v12, 16, v9
	v_mul_f32_e32 v11, v8, v4
	v_mul_f32_e32 v8, 0xbfb8aa3b, v12
	v_mul_f32_e32 v9, 0xbfb8aa3b, v21
	v_exp_f32_e32 v8, v8
	v_exp_f32_e32 v9, v9
	v_rcp_f32_e32 v4, v10
	s_nop 0
	v_mul_f32_e32 v10, v20, v4
	v_pk_mul_f32 v[18:19], v[10:11], v[2:3]
	v_pk_add_f32 v[8:9], v[8:9], 1.0 op_sel_hi:[1,0]
	v_lshlrev_b32_e32 v2, 16, v5
	v_and_b32_e32 v3, 0xffff0000, v5
	v_rcp_f32_e32 v4, v9
	s_nop 0
	v_mul_f32_e32 v5, v21, v4
	v_rcp_f32_e32 v4, v8
	s_nop 0
	v_mul_f32_e32 v4, v12, v4
	ds_read_b128 v[10:13], v164 offset:288
	v_pk_mul_f32 v[20:21], v[4:5], v[2:3]
	v_cvt_pk_bf16_f32 v2, v16, v17
	v_cvt_pk_bf16_f32 v4, v18, v19
	ds_read_b128 v[16:19], v164 offset:416
	s_waitcnt lgkmcnt(1)
	v_lshlrev_b32_e32 v24, 16, v10
	v_and_b32_e32 v10, 0xffff0000, v10
	v_mul_f32_e32 v5, 0xbfb8aa3b, v24
	v_exp_f32_e32 v22, v5
	v_mul_f32_e32 v5, 0xbfb8aa3b, v10
	v_exp_f32_e32 v23, v5
	v_cvt_pk_bf16_f32 v5, v20, v21
	v_cvt_pk_bf16_f32 v3, v6, v7
	ds_read_b128 v[6:9], v164 offset:304
	v_pk_add_f32 v[20:21], v[22:23], 1.0 op_sel_hi:[1,0]
	s_waitcnt lgkmcnt(1)
	v_lshlrev_b32_e32 v22, 16, v16
	v_and_b32_e32 v23, 0xffff0000, v16
	global_store_dwordx4 v[14:15], v[2:5], off offset:16
	ds_read_b128 v[2:5], v164 offset:432
	v_rcp_f32_e32 v16, v21
	v_and_b32_e32 v27, 0xffff0000, v11
	v_mul_f32_e32 v21, v10, v16
	v_lshlrev_b32_e32 v26, 16, v11
	v_mul_f32_e32 v10, 0xbfb8aa3b, v26
	v_mul_f32_e32 v11, 0xbfb8aa3b, v27
	v_exp_f32_e32 v10, v10
	v_exp_f32_e32 v11, v11
	v_rcp_f32_e32 v16, v20
	s_nop 0
	v_mul_f32_e32 v20, v24, v16
	v_pk_mul_f32 v[20:21], v[20:21], v[22:23]
	v_pk_add_f32 v[10:11], v[10:11], 1.0 op_sel_hi:[1,0]
	v_lshlrev_b32_e32 v16, 16, v17
	v_and_b32_e32 v17, 0xffff0000, v17
	v_rcp_f32_e32 v22, v11
	s_nop 0
	v_mul_f32_e32 v11, v27, v22
	v_lshlrev_b32_e32 v27, 16, v12
	v_and_b32_e32 v12, 0xffff0000, v12
	v_mul_f32_e32 v22, 0xbfb8aa3b, v27
	v_mul_f32_e32 v23, 0xbfb8aa3b, v12
	v_exp_f32_e32 v22, v22
	v_exp_f32_e32 v23, v23
	v_rcp_f32_e32 v24, v10
	s_nop 0
	v_mul_f32_e32 v10, v26, v24
	v_pk_mul_f32 v[16:17], v[10:11], v[16:17]
	v_pk_add_f32 v[22:23], v[22:23], 1.0 op_sel_hi:[1,0]
	v_lshlrev_b32_e32 v10, 16, v18
	v_and_b32_e32 v11, 0xffff0000, v18
	v_rcp_f32_e32 v18, v23
	v_and_b32_e32 v26, 0xffff0000, v13
	v_mul_f32_e32 v23, v12, v18
	v_lshlrev_b32_e32 v25, 16, v13
	v_mul_f32_e32 v12, 0xbfb8aa3b, v25
	v_mul_f32_e32 v13, 0xbfb8aa3b, v26
	v_exp_f32_e32 v12, v12
	v_exp_f32_e32 v13, v13
	v_rcp_f32_e32 v18, v22
	s_nop 0
	v_mul_f32_e32 v22, v27, v18
	v_pk_mul_f32 v[22:23], v[22:23], v[10:11]
	v_pk_add_f32 v[12:13], v[12:13], 1.0 op_sel_hi:[1,0]
	v_lshlrev_b32_e32 v10, 16, v19
	v_and_b32_e32 v11, 0xffff0000, v19
	v_rcp_f32_e32 v18, v13
	s_nop 0
	v_mul_f32_e32 v13, v26, v18
	v_rcp_f32_e32 v18, v12
	s_nop 0
	v_mul_f32_e32 v12, v25, v18
	s_waitcnt lgkmcnt(1)
	v_lshlrev_b32_e32 v24, 16, v6
	v_pk_mul_f32 v[18:19], v[12:13], v[10:11]
	v_and_b32_e32 v6, 0xffff0000, v6
	v_mul_f32_e32 v11, 0xbfb8aa3b, v24
	v_cvt_pk_bf16_f32 v10, v20, v21
	v_exp_f32_e32 v20, v11
	v_mul_f32_e32 v11, 0xbfb8aa3b, v6
	v_exp_f32_e32 v21, v11
	v_cvt_pk_bf16_f32 v11, v16, v17
	v_cvt_pk_bf16_f32 v13, v18, v19
	v_cvt_pk_bf16_f32 v12, v22, v23
	v_pk_add_f32 v[16:17], v[20:21], 1.0 op_sel_hi:[1,0]
	global_store_dwordx4 v[14:15], v[10:13], off offset:32
	s_nop 1
	s_waitcnt lgkmcnt(0)
	v_lshlrev_b32_e32 v10, 16, v2
	v_and_b32_e32 v11, 0xffff0000, v2
	v_rcp_f32_e32 v2, v17
	s_nop 0
	v_mul_f32_e32 v13, v6, v2
	v_lshlrev_b32_e32 v17, 16, v7
	v_and_b32_e32 v18, 0xffff0000, v7
	v_mul_f32_e32 v6, 0xbfb8aa3b, v17
	v_mul_f32_e32 v7, 0xbfb8aa3b, v18
	v_exp_f32_e32 v6, v6
	v_exp_f32_e32 v7, v7
	v_rcp_f32_e32 v2, v16
	s_nop 0
	v_mul_f32_e32 v12, v24, v2
	v_pk_mul_f32 v[10:11], v[12:13], v[10:11]
	v_pk_add_f32 v[6:7], v[6:7], 1.0 op_sel_hi:[1,0]
	v_lshlrev_b32_e32 v2, 16, v3
	v_and_b32_e32 v3, 0xffff0000, v3
	v_rcp_f32_e32 v12, v7
	v_lshlrev_b32_e32 v19, 16, v8
	v_mul_f32_e32 v7, v18, v12
	v_and_b32_e32 v8, 0xffff0000, v8
	v_mul_f32_e32 v12, 0xbfb8aa3b, v19
	v_mul_f32_e32 v13, 0xbfb8aa3b, v8
	v_exp_f32_e32 v12, v12
	v_exp_f32_e32 v13, v13
	v_rcp_f32_e32 v16, v6
	s_nop 0
	v_mul_f32_e32 v6, v17, v16
	v_pk_mul_f32 v[6:7], v[6:7], v[2:3]
	v_pk_add_f32 v[12:13], v[12:13], 1.0 op_sel_hi:[1,0]
	v_lshlrev_b32_e32 v2, 16, v4
	v_and_b32_e32 v3, 0xffff0000, v4
	v_rcp_f32_e32 v4, v13
	v_and_b32_e32 v18, 0xffff0000, v9
	v_mul_f32_e32 v13, v8, v4
	v_lshlrev_b32_e32 v16, 16, v9
	v_mul_f32_e32 v8, 0xbfb8aa3b, v16
	v_mul_f32_e32 v9, 0xbfb8aa3b, v18
	v_exp_f32_e32 v8, v8
	v_exp_f32_e32 v9, v9
	v_rcp_f32_e32 v4, v12
	s_nop 0
	v_mul_f32_e32 v12, v19, v4
	v_pk_mul_f32 v[12:13], v[12:13], v[2:3]
	v_pk_add_f32 v[8:9], v[8:9], 1.0 op_sel_hi:[1,0]
	v_lshlrev_b32_e32 v2, 16, v5
	v_and_b32_e32 v3, 0xffff0000, v5
	v_rcp_f32_e32 v4, v9
	s_nop 0
	v_mul_f32_e32 v5, v18, v4
	v_rcp_f32_e32 v4, v8
	s_nop 0
	v_mul_f32_e32 v4, v16, v4
	v_pk_mul_f32 v[8:9], v[4:5], v[2:3]
	v_cvt_pk_bf16_f32 v2, v10, v11
	v_cvt_pk_bf16_f32 v3, v6, v7
	v_cvt_pk_bf16_f32 v4, v12, v13
	v_cvt_pk_bf16_f32 v5, v8, v9
	global_store_dwordx4 v[14:15], v[2:5], off offset:48
	s_branch .LBB0_289
